# strategy 7 (guide 7.5): all 512 packed fp32 VOP3P ops of the attention phase split into scalar VALU ops (bit-identical)
# speedup vs baseline: 1.0070x; 1.0043x over previous
; template <int DV, bool FOX>
; DI void flash(f32x16 (&O)[DV / 32], const bf16_t* __restrict__ qptr, const bf16_t* __restrict__ kg, const bf16_t* __restrict__ vtg,
;               int ntiles, int q, float slope2, const float* __restrict__ cum2, float KN, bf16_t* smem) {
;     ...
;         const bf16_t* Ks = smem + (cur * 2 + pj) * BUF; const bf16_t* Vs = Ks + KS_ELEMS;
;         const int kb = kt * 64;
;         const float cklast = pj ? ckl1 : ckl0;
;         if (kb < wkend && !wskip) {
;         f32x16 s[2];
; #pragma unroll
;         for (int sub = 0; sub < 2; ++sub) {
;             s[sub] = zero16();
; #pragma unroll
;             for (int ks = 0; ks < 4; ++ks) {
;                 const bf16x8 a = *(const bf16x8*)(Ks + (sub * 32 + pr) * 72 + ks * 16 + h * 8);
;                 s[sub] = mfma32(a, qf[ks], s[sub]);
;             }
;         }
;         float mx = -INFINITY;
;         if (kb + 63 < qlo) {
; #pragma unroll
;             for (int sub = 0; sub < 2; ++sub) {
; #pragma unroll
;                 for (int i8 = 0; i8 < 2; ++i8) {
;                     const int k0 = kb + sub * 32 + 16 * i8 + 8 * h;
;                     float ck[8];
;                     float base = 0.f;
;                     if (FOX) {
;                         const f32x4 c0 = *(const f32x4*)(cum2 + k0), c1v = *(const f32x4*)(cum2 + k0 + 4);
;                         ck[0] = c0[0]; ck[1] = c0[1]; ck[2] = c0[2]; ck[3] = c0[3]; ck[4] = c1v[0]; ck[5] = c1v[1]; ck[6] = c1v[2]; ck[7] = c1v[3];
;                     } else base = -slope2 * (float)(q - k0);
; #pragma unroll
;                     for (int e = 0; e < 8; ++e) {
;                         const float bias = FOX ? cq - ck[e] : fmaf(slope2, (float)e, base);
;                         const float t = fmaf(s[sub][8 * i8 + e], c1, bias);
;                         s[sub][8 * i8 + e] = t;
;                         mx = fmaxf(mx, t);
;                     }
;                 }
;             }
;         } else {
; #pragma unroll
;             for (int sub = 0; sub < 2; ++sub) {
; #pragma unroll
;                 for (int i8 = 0; i8 < 2; ++i8) {
;                     const int k0 = kb + sub * 32 + 16 * i8 + 8 * h;
;                     float ck[8];
;                     if (FOX) {
;                         const f32x4 c0 = *(const f32x4*)(cum2 + k0), c1v = *(const f32x4*)(cum2 + k0 + 4);
.LBB0_615:
	s_sub_i32 s74, s42, s80
	s_cmp_gt_i32 s74, -1
	s_cselect_b64 s[72:73], -1, 0
	s_cmp_lt_i32 s74, 0
	s_cbranch_scc1 .LBB0_624
	s_lshl_b32 s78, s74, 6
	s_cmp_gt_i32 s78, s96
	s_cselect_b64 s[74:75], -1, 0
	s_or_b64 s[74:75], s[74:75], s[10:11]
	s_and_b64 vcc, exec, s[74:75]
	s_cbranch_vccnz .LBB0_625
	s_or_b32 s74, s80, s43
	s_mulk_i32 s74, 0x6c00
	v_add_u32_e32 v142, s74, v226
	v_add_u32_e32 v151, v142, v221
	ds_read_b128 v[68:71], v151
	ds_read_b128 v[72:75], v151 offset:32
	s_or_b32 vcc_lo, s78, 63
	s_mov_b64 s[74:75], -1
	s_cmp_lt_i32 vcc_lo, s95
	s_waitcnt lgkmcnt(1)
	v_mfma_f32_32x32x16_bf16 v[84:99], v[68:71], v[100:103], 0
	ds_read_b128 v[68:71], v151 offset:64
	ds_read_b128 v[178:181], v151 offset:4640
	s_waitcnt lgkmcnt(2)
	v_mfma_f32_32x32x16_bf16 v[84:99], v[72:75], v[104:107], v[84:99]
	s_waitcnt lgkmcnt(1)
	v_mfma_f32_32x32x16_bf16 v[84:99], v[68:71], v[108:111], v[84:99]
	ds_read_b128 v[68:71], v151 offset:96
	s_waitcnt lgkmcnt(0)
	v_mfma_f32_32x32x16_bf16 v[84:99], v[68:71], v[112:115], v[84:99]
	ds_read_b128 v[68:71], v151 offset:4608
	s_waitcnt lgkmcnt(0)
	v_mfma_f32_32x32x16_bf16 v[68:83], v[68:71], v[100:103], 0
	v_mfma_f32_32x32x16_bf16 v[68:83], v[178:181], v[104:107], v[68:83]
	ds_read_b128 v[178:181], v151 offset:4672
	s_waitcnt lgkmcnt(0)
	v_mfma_f32_32x32x16_bf16 v[68:83], v[178:181], v[108:111], v[68:83]
	ds_read_b128 v[178:181], v151 offset:4704
	s_waitcnt lgkmcnt(0)
	v_mfma_f32_32x32x16_bf16 v[68:83], v[178:181], v[112:115], v[68:83]
	s_cbranch_scc1 .LBB0_619
	v_or_b32_e32 v173, s78, v169
	v_or_b32_e32 v151, 1, v173
	v_sub_u32_e32 v158, v154, v173
	v_sub_u32_e32 v178, v145, v151
	v_cvt_f32_i32_e32 v158, v158
	v_cvt_f32_i32_e32 v179, v178
	v_cmp_lt_i32_e32 vcc, v151, v67
	v_or_b32_e32 v151, 3, v173
	v_and_b32_e32 v178, 0x7fffffff, v158
	v_or_b32_e32 v158, 2, v173
	v_and_b32_e32 v179, 0x7fffffff, v179
	v_sub_u32_e32 v180, v145, v151
	v_sub_u32_e32 v181, v154, v158
	v_mul_f32_e64 v178, v176, v178
	v_mul_f32_e64 v179, v177, v179
	v_cvt_f32_i32_e32 v182, v181
	v_cvt_f32_i32_e32 v180, v180
	v_fma_f32 v178, v84, s24, -v178
	v_fma_f32 v179, v85, s24, -v179
	v_or_b32_e32 v184, 4, v173
	v_cndmask_b32_e32 v179, v216, v179, vcc
	v_cmp_lt_i32_e32 vcc, v173, v162
	v_and_b32_e32 v181, 0x7fffffff, v180
	v_and_b32_e32 v180, 0x7fffffff, v182
	v_cndmask_b32_e32 v178, v216, v178, vcc
	v_cmp_lt_i32_e32 vcc, v151, v67
	v_or_b32_e32 v151, 5, v173
	v_sub_u32_e32 v182, v145, v151
	v_sub_u32_e32 v185, v154, v184
	v_mul_f32_e64 v180, v176, v180
	v_mul_f32_e64 v181, v177, v181
	v_cvt_f32_i32_e32 v185, v185
	v_cvt_f32_i32_e32 v182, v182
	v_fma_f32 v180, v86, s24, -v180
	v_fma_f32 v181, v87, s24, -v181
	v_max3_f32 v183, v178, s89, v179
	v_cndmask_b32_e32 v181, v216, v181, vcc
	v_cmp_lt_i32_e32 vcc, v158, v162
	v_or_b32_e32 v186, 6, v173
	v_sub_u32_e32 v187, v154, v186
	v_cndmask_b32_e32 v180, v216, v180, vcc
	v_cmp_lt_i32_e32 vcc, v151, v67
	v_or_b32_e32 v151, 7, v173
	v_max3_f32 v158, v183, v180, v181
	v_and_b32_e32 v183, 0x7fffffff, v182
	v_and_b32_e32 v182, 0x7fffffff, v185
	v_sub_u32_e32 v185, v145, v151
	v_mul_f32_e64 v182, v176, v182
	v_mul_f32_e64 v183, v177, v183
	v_cvt_f32_i32_e32 v187, v187
	v_cvt_f32_i32_e32 v185, v185
	v_fma_f32 v182, v88, s24, -v182
	v_fma_f32 v183, v89, s24, -v183
	v_or_b32_e32 v190, 18, v173
	v_cndmask_b32_e32 v183, v216, v183, vcc
	v_cmp_lt_i32_e32 vcc, v184, v162
	v_and_b32_e32 v185, 0x7fffffff, v185
	v_and_b32_e32 v184, 0x7fffffff, v187
	v_cndmask_b32_e32 v182, v216, v182, vcc
	v_cmp_lt_i32_e32 vcc, v151, v67
	v_or_b32_e32 v151, 17, v173
	v_sub_u32_e32 v187, v164, v173
	v_sub_u32_e32 v188, v161, v151
	v_mul_f32_e64 v184, v176, v184
	v_mul_f32_e64 v185, v177, v185
	v_cvt_f32_i32_e32 v188, v188
	v_cvt_f32_i32_e32 v187, v187
	v_fma_f32 v184, v90, s24, -v184
	v_fma_f32 v185, v91, s24, -v185
	v_sub_u32_e32 v189, v154, v190
	v_cndmask_b32_e32 v185, v216, v185, vcc
	v_cmp_lt_i32_e32 vcc, v186, v162
	v_and_b32_e32 v186, 0x7fffffff, v187
	v_and_b32_e32 v187, 0x7fffffff, v188
	v_cndmask_b32_e32 v184, v216, v184, vcc
	v_cmp_lt_i32_e32 vcc, v151, v155
	v_or_b32_e32 v151, 19, v173
	v_sub_u32_e32 v188, v145, v151
	v_mul_f32_e64 v186, v176, v186
	v_mul_f32_e64 v187, v177, v187
	v_cvt_f32_i32_e32 v191, v189
	v_cvt_f32_i32_e32 v188, v188
	v_fma_f32 v186, v92, s24, -v186
	v_fma_f32 v187, v93, s24, -v187
	v_or_b32_e32 v192, 20, v173
	v_cndmask_b32_e32 v187, v216, v187, vcc
	v_cmp_lt_i32_e32 vcc, v173, v160
	v_and_b32_e32 v189, 0x7fffffff, v188
	v_and_b32_e32 v188, 0x7fffffff, v191
	v_cndmask_b32_e32 v186, v216, v186, vcc
	v_cmp_lt_i32_e32 vcc, v151, v67
	v_or_b32_e32 v151, 21, v173
	v_sub_u32_e32 v191, v145, v151
	v_sub_u32_e32 v193, v154, v192
	v_cvt_f32_i32_e32 v193, v193
	v_cvt_f32_i32_e32 v191, v191
	v_mul_f32_e64 v188, v176, v188
	v_mul_f32_e64 v189, v177, v189
	v_or_b32_e32 v194, 22, v173
	v_fma_f32 v188, v94, s24, -v188
	v_fma_f32 v189, v95, s24, -v189
	v_and_b32_e32 v191, 0x7fffffff, v191
	v_cndmask_b32_e32 v189, v216, v189, vcc
	v_cmp_lt_i32_e32 vcc, v190, v162
	v_and_b32_e32 v190, 0x7fffffff, v193
	v_sub_u32_e32 v195, v154, v194
	v_cndmask_b32_e32 v188, v216, v188, vcc
	v_cmp_lt_i32_e32 vcc, v151, v67
	v_or_b32_e32 v151, 23, v173
	v_mul_f32_e64 v190, v176, v190
	v_mul_f32_e64 v191, v177, v191
	v_sub_u32_e32 v193, v145, v151
	v_cvt_f32_i32_e32 v195, v195
	v_fma_f32 v190, v96, s24, -v190
	v_fma_f32 v191, v97, s24, -v191
	v_cvt_f32_i32_e32 v193, v193
	v_cndmask_b32_e32 v191, v216, v191, vcc
	v_cmp_lt_i32_e32 vcc, v192, v162
	v_or_b32_e32 v196, 32, v173
	v_and_b32_e32 v192, 0x7fffffff, v195
	v_cndmask_b32_e32 v190, v216, v190, vcc
	v_cmp_lt_i32_e32 vcc, v151, v67
	v_or_b32_e32 v151, 33, v173
; template <int DV, bool FOX>
; DI void flash(f32x16 (&O)[DV / 32], const bf16_t* __restrict__ qptr, const bf16_t* __restrict__ kg, const bf16_t* __restrict__ vtg,
;               int ntiles, int q, float slope2, const float* __restrict__ cum2, float KN, bf16_t* smem) {
;     ...
;         } else {
; #pragma unroll
;             for (int sub = 0; sub < 2; ++sub) {
; #pragma unroll
;                 for (int i8 = 0; i8 < 2; ++i8) {
;                     const int k0 = kb + sub * 32 + 16 * i8 + 8 * h;
;                     float ck[8];
;                     if (FOX) {
;                         const f32x4 c0 = *(const f32x4*)(cum2 + k0), c1v = *(const f32x4*)(cum2 + k0 + 4);
;                         ck[0] = c0[0]; ck[1] = c0[1]; ck[2] = c0[2]; ck[3] = c0[3]; ck[4] = c1v[0]; ck[5] = c1v[1]; ck[6] = c1v[2]; ck[7] = c1v[3];
;                     }
; #pragma unroll
;                     for (int e = 0; e < 8; ++e) {
;                         const int k = k0 + e;
;                         float t = s[sub][8 * i8 + e] * c1;
;                         if (FOX) t += cq - ck[e];
;                         else t -= slope2 * fabsf((float)(q - k));
;                         t = (k < kend) ? t : -INFINITY;
;                         s[sub][8 * i8 + e] = t;
;                         mx = fmaxf(mx, t);
;                     }
;                 }
;             }
	v_sub_u32_e32 v195, v145, v151
	v_sub_u32_e32 v197, v154, v196
	v_and_b32_e32 v193, 0x7fffffff, v193
	v_cvt_f32_i32_e32 v197, v197
	v_cvt_f32_i32_e32 v195, v195
	v_mul_f32_e64 v192, v176, v192
	v_mul_f32_e64 v193, v177, v193
	v_or_b32_e32 v198, 34, v173
	v_fma_f32 v192, v98, s24, -v192
	v_fma_f32 v193, v99, s24, -v193
	v_and_b32_e32 v195, 0x7fffffff, v195
	v_cndmask_b32_e32 v193, v216, v193, vcc
	v_cmp_lt_i32_e32 vcc, v194, v162
	v_and_b32_e32 v194, 0x7fffffff, v197
	v_sub_u32_e32 v199, v154, v198
	v_cndmask_b32_e32 v192, v216, v192, vcc
	v_cmp_lt_i32_e32 vcc, v151, v67
	v_or_b32_e32 v151, 35, v173
	v_mul_f32_e64 v194, v176, v194
	v_mul_f32_e64 v195, v177, v195
	v_sub_u32_e32 v197, v145, v151
	v_cvt_f32_i32_e32 v199, v199
	v_fma_f32 v194, v68, s24, -v194
	v_fma_f32 v195, v69, s24, -v195
	v_cvt_f32_i32_e32 v197, v197
	v_cndmask_b32_e32 v195, v216, v195, vcc
	v_cmp_lt_i32_e32 vcc, v196, v162
	v_or_b32_e32 v200, 36, v173
	v_and_b32_e32 v196, 0x7fffffff, v199
	v_cndmask_b32_e32 v194, v216, v194, vcc
	v_cmp_lt_i32_e32 vcc, v151, v67
	v_or_b32_e32 v151, 37, v173
	v_sub_u32_e32 v199, v145, v151
	v_sub_u32_e32 v201, v154, v200
	v_and_b32_e32 v197, 0x7fffffff, v197
	v_cvt_f32_i32_e32 v201, v201
	v_cvt_f32_i32_e32 v199, v199
	v_max3_f32 v158, v158, v182, v183
	v_mul_f32_e64 v196, v176, v196
	v_mul_f32_e64 v197, v177, v197
	v_max3_f32 v158, v158, v184, v185
	v_fma_f32 v196, v70, s24, -v196
	v_fma_f32 v197, v71, s24, -v197
	v_max3_f32 v158, v158, v186, v187
	v_cndmask_b32_e32 v197, v216, v197, vcc
	v_cmp_lt_i32_e32 vcc, v198, v162
	v_or_b32_e32 v208, 38, v173
	v_max3_f32 v158, v158, v188, v189
	v_cndmask_b32_e32 v196, v216, v196, vcc
	v_and_b32_e32 v199, 0x7fffffff, v199
	v_and_b32_e32 v198, 0x7fffffff, v201
	v_cmp_lt_i32_e32 vcc, v151, v67
	v_or_b32_e32 v207, 39, v173
	v_sub_u32_e32 v151, v154, v208
	v_max3_f32 v158, v158, v190, v191
	v_mul_f32_e64 v198, v176, v198
	v_mul_f32_e64 v199, v177, v199
	v_cvt_f32_i32_e32 v151, v151
	v_sub_u32_e32 v201, v154, v207
	v_max3_f32 v158, v158, v192, v193
	v_fma_f32 v198, v72, s24, -v198
	v_fma_f32 v199, v73, s24, -v199
	v_cvt_f32_i32_e32 v204, v201
	v_max3_f32 v158, v158, v194, v195
	v_cndmask_b32_e32 v199, v216, v199, vcc
	v_cmp_lt_i32_e32 vcc, v200, v162
	v_max3_f32 v158, v158, v196, v197
	v_and_b32_e32 v151, 0x7fffffff, v151
	v_cndmask_b32_e32 v198, v216, v198, vcc
	v_max3_f32 v206, v158, v198, v199
	v_mov_b32_e32 v158, v74
	v_mov_b32_e32 v200, v75
	v_mov_b32_e32 v201, v159
	v_mul_f32_e64 v202, v158, v150
	v_mul_f32_e64 v203, v159, v151
	v_and_b32_e32 v151, 0x7fffffff, v204
	v_mul_f32_e64 v200, v200, v150
	v_mul_f32_e64 v201, v201, v151
	v_mov_b32_e32 v204, v202
	v_mov_b32_e32 v205, v200
	v_mov_b32_e32 v200, v203
	v_add_f32_e64 v200, v204, -v200
	v_add_f32_e64 v201, v205, -v201
	v_cmp_lt_i32_e32 vcc, v207, v67
	v_or_b32_e32 v228, 48, v173
	v_or_b32_e32 v209, 49, v173
	v_cndmask_b32_e32 v201, v216, v201, vcc
	v_cmp_lt_i32_e32 vcc, v208, v162
	v_sub_u32_e32 v151, v154, v228
	v_cvt_f32_i32_e32 v151, v151
	v_cndmask_b32_e32 v200, v216, v200, vcc
	v_sub_u32_e32 v203, v154, v209
	v_max3_f32 v208, v206, v200, v201
	v_cvt_f32_i32_e32 v206, v203
	v_mov_b32_e32 v158, v76
	v_and_b32_e32 v151, 0x7fffffff, v151
	v_mov_b32_e32 v202, v77
	v_mov_b32_e32 v203, v159
	v_mul_f32_e64 v204, v158, v150
	v_mul_f32_e64 v205, v159, v151
	v_and_b32_e32 v151, 0x7fffffff, v206
	v_mul_f32_e64 v202, v202, v150
	v_mul_f32_e64 v203, v203, v151
	v_mov_b32_e32 v206, v204
	v_mov_b32_e32 v207, v202
	v_mov_b32_e32 v202, v205
	v_add_f32_e64 v202, v206, -v202
	v_add_f32_e64 v203, v207, -v203
	v_cmp_lt_i32_e32 vcc, v209, v67
	v_or_b32_e32 v230, 50, v173
	v_or_b32_e32 v229, 51, v173
	v_cndmask_b32_e32 v205, v216, v203, vcc
	v_cmp_lt_i32_e32 vcc, v228, v162
	v_sub_u32_e32 v151, v154, v230
	v_cvt_f32_i32_e32 v151, v151
	v_cndmask_b32_e32 v204, v216, v202, vcc
	v_sub_u32_e32 v203, v154, v229
	v_max3_f32 v228, v208, v204, v205
	v_cvt_f32_i32_e32 v208, v203
	v_mov_b32_e32 v158, v78
	v_and_b32_e32 v151, 0x7fffffff, v151
	v_mov_b32_e32 v202, v79
	v_mov_b32_e32 v203, v159
	v_mul_f32_e64 v206, v158, v150
	v_mul_f32_e64 v207, v159, v151
	v_and_b32_e32 v151, 0x7fffffff, v208
	v_mul_f32_e64 v202, v202, v150
	v_mul_f32_e64 v203, v203, v151
	v_mov_b32_e32 v208, v206
	v_mov_b32_e32 v209, v202
	v_mov_b32_e32 v202, v207
	v_add_f32_e64 v202, v208, -v202
	v_add_f32_e64 v203, v209, -v203
	v_cmp_lt_i32_e32 vcc, v229, v67
	v_or_b32_e32 v232, 52, v173
	v_or_b32_e32 v231, 53, v173
	v_cndmask_b32_e32 v203, v216, v203, vcc
	v_cmp_lt_i32_e32 vcc, v230, v162
	v_sub_u32_e32 v151, v154, v232
	v_cvt_f32_i32_e32 v151, v151
	v_cndmask_b32_e32 v202, v216, v202, vcc
	v_sub_u32_e32 v207, v154, v231
	v_max3_f32 v230, v228, v202, v203
	v_cvt_f32_i32_e32 v228, v207
	v_mov_b32_e32 v158, v80
	v_and_b32_e32 v151, 0x7fffffff, v151
	v_mov_b32_e32 v206, v81
	v_mov_b32_e32 v207, v159
	v_mul_f32_e64 v208, v158, v150
	v_mul_f32_e64 v209, v159, v151
	v_and_b32_e32 v151, 0x7fffffff, v228
	v_mul_f32_e64 v206, v206, v150
	v_mul_f32_e64 v207, v207, v151
	v_mov_b32_e32 v228, v208
	v_mov_b32_e32 v229, v206
	v_mov_b32_e32 v206, v209
	v_add_f32_e64 v206, v228, -v206
	v_add_f32_e64 v207, v229, -v207
	v_cmp_lt_i32_e32 vcc, v231, v67
	v_or_b32_e32 v233, 55, v173
	v_or_b32_e32 v173, 54, v173
	v_cndmask_b32_e32 v207, v216, v207, vcc
	v_cmp_lt_i32_e32 vcc, v232, v162
	v_sub_u32_e32 v151, v154, v173
	v_cvt_f32_i32_e32 v151, v151
	v_cndmask_b32_e32 v206, v216, v206, vcc
	v_sub_u32_e32 v209, v154, v233
	v_max3_f32 v232, v230, v206, v207
	v_cvt_f32_i32_e32 v230, v209
	v_mov_b32_e32 v158, v82
	v_and_b32_e32 v151, 0x7fffffff, v151
	v_mov_b32_e32 v208, v83
	v_mov_b32_e32 v209, v159
	v_mul_f32_e64 v228, v158, v150
	v_mul_f32_e64 v229, v159, v151
	v_and_b32_e32 v151, 0x7fffffff, v230
	v_mul_f32_e64 v208, v208, v150
	v_mul_f32_e64 v209, v209, v151
	v_mov_b32_e32 v230, v228
	v_mov_b32_e32 v231, v208
	v_mov_b32_e32 v208, v229
	v_add_f32_e64 v208, v230, -v208
	v_add_f32_e64 v209, v231, -v209
	v_cmp_lt_i32_e32 vcc, v233, v67
	s_mov_b64 s[74:75], 0
	s_nop 0
	v_cndmask_b32_e32 v209, v216, v209, vcc
	v_cmp_lt_i32_e32 vcc, v173, v162
	s_nop 1
	v_cndmask_b32_e32 v208, v216, v208, vcc
	v_max3_f32 v151, v232, v208, v209
; template <int DV, bool FOX>
; DI void flash(f32x16 (&O)[DV / 32], const bf16_t* __restrict__ qptr, const bf16_t* __restrict__ kg, const bf16_t* __restrict__ vtg,
;               int ntiles, int q, float slope2, const float* __restrict__ cum2, float KN, bf16_t* smem) {
;     ...
;         if (kb + 63 < qlo) {
; #pragma unroll
;             for (int sub = 0; sub < 2; ++sub) {
; #pragma unroll
;                 for (int i8 = 0; i8 < 2; ++i8) {
;                     const int k0 = kb + sub * 32 + 16 * i8 + 8 * h;
;                     float ck[8];
;                     float base = 0.f;
;                     if (FOX) {
;                         const f32x4 c0 = *(const f32x4*)(cum2 + k0), c1v = *(const f32x4*)(cum2 + k0 + 4);
;                         ck[0] = c0[0]; ck[1] = c0[1]; ck[2] = c0[2]; ck[3] = c0[3]; ck[4] = c1v[0]; ck[5] = c1v[1]; ck[6] = c1v[2]; ck[7] = c1v[3];
;                     } else base = -slope2 * (float)(q - k0);
; #pragma unroll
;                     for (int e = 0; e < 8; ++e) {
;                         const float bias = FOX ? cq - ck[e] : fmaf(slope2, (float)e, base);
;                         const float t = fmaf(s[sub][8 * i8 + e], c1, bias);
;                         s[sub][8 * i8 + e] = t;
;                         mx = fmaxf(mx, t);
;                     }
;                 }
;             }
;         } else {
; #pragma unroll
;             for (int sub = 0; sub < 2; ++sub) {
; #pragma unroll
;                 for (int i8 = 0; i8 < 2; ++i8) {
;                     const int k0 = kb + sub * 32 + 16 * i8 + 8 * h;
;                     float ck[8];
;                     if (FOX) {
;                         const f32x4 c0 = *(const f32x4*)(cum2 + k0), c1v = *(const f32x4*)(cum2 + k0 + 4);
;                         ck[0] = c0[0]; ck[1] = c0[1]; ck[2] = c0[2]; ck[3] = c0[3]; ck[4] = c1v[0]; ck[5] = c1v[1]; ck[6] = c1v[2]; ck[7] = c1v[3];
;                     }
; #pragma unroll
;                     for (int e = 0; e < 8; ++e) {
;                         const int k = k0 + e;
;                         float t = s[sub][8 * i8 + e] * c1;
;                         if (FOX) t += cq - ck[e];
;                         else t -= slope2 * fabsf((float)(q - k));
;                         t = (k < kend) ? t : -INFINITY;
;                         s[sub][8 * i8 + e] = t;
;                         mx = fmaxf(mx, t);
;                     }
.LBB0_619:
	s_andn2_b64 vcc, exec, s[74:75]
	s_cbranch_vccnz .LBB0_621
	v_subrev_u32_e32 v151, s78, v154
	v_add_u32_e32 v158, v151, v220
	v_cvt_f32_i32_e32 v173, v158
	v_mul_f32_e64 v158, -v159, v173
	v_fma_f32 v179, -v159, v173, v159
	v_fma_f32 v178, 0, v159, v158
	v_fma_f32 v180, v176, s26, v158
	v_fma_f32 v181, v177, s27, v158
	v_fma_f32 v178, v84, s24, v178
	v_fma_f32 v179, v85, s24, v179
	v_fma_f32 v180, v86, s24, v180
	v_fma_f32 v181, v87, s24, v181
	v_max3_f32 v84, v178, s89, v179
	v_max3_f32 v86, v84, v180, v181
	v_fma_f32 v84, v176, s28, v158
	v_fma_f32 v85, v177, s29, v158
	s_nop 0
	v_fma_f32 v182, v88, s24, v84
	v_fma_f32 v183, v89, s24, v85
	v_add_u32_e32 v84, v222, v151
	v_cvt_f32_i32_e32 v87, v84
	v_fma_f32 v84, v176, s48, v158
	v_fma_f32 v85, v177, s49, v158
	v_max3_f32 v86, v86, v182, v183
	v_fma_f32 v184, v90, s24, v84
	v_fma_f32 v185, v91, s24, v85
	v_mul_f32_e64 v84, -v159, v87
	v_max3_f32 v85, v86, v184, v185
	v_fma_f32 v86, 0, v159, v84
	v_fma_f32 v87, -v159, v87, v159
	v_fma_f32 v186, v92, s24, v86
	v_fma_f32 v187, v93, s24, v87
	s_nop 0
	v_max3_f32 v85, v85, v186, v187
	v_fma_f32 v86, v176, s26, v84
	v_fma_f32 v87, v177, s27, v84
	s_nop 0
	v_fma_f32 v188, v94, s24, v86
	v_fma_f32 v189, v95, s24, v87
	s_nop 0
	v_max3_f32 v85, v85, v188, v189
	v_fma_f32 v86, v176, s28, v84
	v_fma_f32 v87, v177, s29, v84
	s_nop 0
	v_fma_f32 v190, v96, s24, v86
	v_fma_f32 v191, v97, s24, v87
	s_nop 0
	v_max3_f32 v86, v85, v190, v191
	v_add_u32_e32 v85, v223, v151
	v_cvt_f32_i32_e32 v87, v85
	v_fma_f32 v85, v177, s49, v84
	v_fma_f32 v84, v176, s48, v84
	s_nop 0
	v_fma_f32 v192, v98, s24, v84
	v_fma_f32 v193, v99, s24, v85
	v_mul_f32_e64 v84, -v159, v87
	v_max3_f32 v85, v86, v192, v193
	v_fma_f32 v86, 0, v159, v84
	v_fma_f32 v87, -v159, v87, v159
	v_fma_f32 v194, v68, s24, v86
	v_fma_f32 v195, v69, s24, v87
	s_nop 0
	v_max3_f32 v85, v85, v194, v195
	v_fma_f32 v68, v176, s26, v84
	v_fma_f32 v69, v177, s27, v84
	s_nop 0
	v_fma_f32 v196, v70, s24, v68
	v_fma_f32 v197, v71, s24, v69
	v_fma_f32 v68, v176, s28, v84
	v_fma_f32 v69, v177, s29, v84
	v_max3_f32 v70, v85, v196, v197
	v_fma_f32 v198, v72, s24, v68
	v_fma_f32 v199, v73, s24, v69
	v_add_u32_e32 v68, v224, v151
	v_cvt_f32_i32_e32 v71, v68
	v_fma_f32 v68, v176, s48, v84
	v_fma_f32 v69, v177, s49, v84
	v_max3_f32 v70, v70, v198, v199
	v_fma_f32 v200, v74, s24, v68
	v_fma_f32 v201, v75, s24, v69
	v_mul_f32_e64 v68, -v159, v71
	v_max3_f32 v69, v70, v200, v201
	v_fma_f32 v70, 0, v159, v68
	v_fma_f32 v71, -v159, v71, v159
	v_fma_f32 v204, v76, s24, v70
	v_fma_f32 v205, v77, s24, v71
	s_nop 0
	v_max3_f32 v69, v69, v204, v205
	v_fma_f32 v70, v176, s26, v68
	v_fma_f32 v71, v177, s27, v68
	s_nop 0
	v_fma_f32 v202, v78, s24, v70
	v_fma_f32 v203, v79, s24, v71
	s_nop 0
	v_max3_f32 v69, v69, v202, v203
	v_fma_f32 v70, v176, s28, v68
	v_fma_f32 v71, v177, s29, v68
	s_nop 0
	v_fma_f32 v206, v80, s24, v70
	v_fma_f32 v207, v81, s24, v71
	s_nop 0
	v_max3_f32 v70, v69, v206, v207
	v_fma_f32 v69, v177, s49, v68
	v_fma_f32 v68, v176, s48, v68
	s_nop 0
	v_fma_f32 v208, v82, s24, v68
	v_fma_f32 v209, v83, s24, v69
	s_nop 0
	v_max3_f32 v151, v70, v208, v209
.LBB0_621:
	s_nop 8
	v_mov_b32_e32 v68, v151
	s_nop 1
	v_permlane32_swap_b32_e32 v151, v68
	v_max3_f32 v173, v227, v151, v68
	v_cmp_gt_f32_e32 vcc, v173, v227
	s_cbranch_vccz .LBB0_623
	v_sub_f32_e32 v68, v227, v173
	v_exp_f32_e32 v68, v68
	s_nop 0
	v_mul_f32_e64 v64, v64, v68
	v_mul_f32_e64 v65, v65, v68
	v_mul_f32_e64 v62, v62, v68
	v_mul_f32_e64 v63, v63, v68
	v_mul_f32_e64 v60, v60, v68
	v_mul_f32_e64 v61, v61, v68
	v_mul_f32_e64 v58, v58, v68
	v_mul_f32_e64 v59, v59, v68
	v_mul_f32_e64 v56, v56, v68
	v_mul_f32_e64 v57, v57, v68
	v_mul_f32_e64 v54, v54, v68
	v_mul_f32_e64 v55, v55, v68
	v_mul_f32_e64 v52, v52, v68
	v_mul_f32_e64 v53, v53, v68
	v_mul_f32_e64 v50, v50, v68
	v_mul_f32_e64 v51, v51, v68
	v_mul_f32_e64 v48, v48, v68
	v_mul_f32_e64 v49, v49, v68
	v_mul_f32_e64 v46, v46, v68
	v_mul_f32_e64 v47, v47, v68
	v_mul_f32_e64 v44, v44, v68
	v_mul_f32_e64 v45, v45, v68
	v_mul_f32_e64 v42, v42, v68
	v_mul_f32_e64 v43, v43, v68
	v_mul_f32_e64 v40, v40, v68
	v_mul_f32_e64 v41, v41, v68
	v_mul_f32_e64 v38, v38, v68
	v_mul_f32_e64 v39, v39, v68
	v_mul_f32_e64 v36, v36, v68
	v_mul_f32_e64 v37, v37, v68
	v_mul_f32_e64 v34, v34, v68
	v_mul_f32_e64 v35, v35, v68
	v_mul_f32_e64 v32, v32, v68
	v_mul_f32_e64 v33, v33, v68
	v_mul_f32_e64 v30, v30, v68
	v_mul_f32_e64 v31, v31, v68
	v_mul_f32_e64 v28, v28, v68
	v_mul_f32_e64 v29, v29, v68
	v_mul_f32_e64 v26, v26, v68
	v_mul_f32_e64 v27, v27, v68
	v_mul_f32_e64 v24, v24, v68
	v_mul_f32_e64 v25, v25, v68
	v_mul_f32_e64 v22, v22, v68
	v_mul_f32_e64 v23, v23, v68
	v_mul_f32_e64 v20, v20, v68
	v_mul_f32_e64 v21, v21, v68
	v_mul_f32_e64 v18, v18, v68
	v_mul_f32_e64 v19, v19, v68
	v_mul_f32_e64 v16, v16, v68
	v_mul_f32_e64 v17, v17, v68
	v_mul_f32_e64 v14, v14, v68
	v_mul_f32_e64 v15, v15, v68
	v_mul_f32_e64 v12, v12, v68
	v_mul_f32_e64 v13, v13, v68
	v_mul_f32_e64 v10, v10, v68
	v_mul_f32_e64 v11, v11, v68
	v_mul_f32_e64 v8, v8, v68
	v_mul_f32_e64 v9, v9, v68
	v_mul_f32_e64 v6, v6, v68
	v_mul_f32_e64 v7, v7, v68
	v_mul_f32_e64 v4, v4, v68
	v_mul_f32_e64 v5, v5, v68
	v_mul_f32_e64 v2, v2, v68
	v_mul_f32_e64 v3, v3, v68
	v_mul_f32_e32 v66, v66, v68

; template <int DV, bool FOX>
; DI void flash(f32x16 (&O)[DV / 32], const bf16_t* __restrict__ qptr, const bf16_t* __restrict__ kg, const bf16_t* __restrict__ vtg,
;               int ntiles, int q, float slope2, const float* __restrict__ cum2, float KN, bf16_t* smem) {
;     ...
;         if (kt > 0) {
;             const int klast = kb - 1;
;             float bm = 0.f;
;             if (klast < q) bm = FOX ? cq - cklast : -slope2 * (float)(q - klast);
;             const bool pred = (q >= LT) || (sbound + bm < m - 152.f);
;             wskip = __all(pred);
;         }
.LBB0_626:
	v_subrev_u32_e32 v68, s78, v163
	v_cvt_f32_i32_e32 v68, v68
	v_cmp_le_i32_e32 vcc, s78, v154
	v_mul_f32_e64 v68, -v159, v68
	s_nop 0
	v_cndmask_b32_e32 v142, 0, v68, vcc
	v_add_f32_e64 v68, v172, v142
	v_add_f32_e64 v69, v173, v143
	s_nop 0
	v_cmp_lt_f32_e32 vcc, v68, v69
	s_or_b64 s[10:11], s[4:5], vcc
	v_cndmask_b32_e64 v68, 0, 1, s[10:11]
	v_cmp_ne_u32_e32 vcc, 0, v68
	s_cmp_eq_u64 vcc, exec
	s_cselect_b64 s[10:11], -1, 0

; DI f32x16 zero16() { f32x16 z; for (int i = 0; i < 16; ++i) z[i] = 0.f; return z; }
; DI float xsum32(float x) { auto r = __builtin_amdgcn_permlane32_swap(__float_as_uint(x), __float_as_uint(x), false, false); return __uint_as_float(r[0]) + __uint_as_float(r[1]); }
; template <int DV, bool FOX>
; DI void flash(f32x16 (&O)[DV / 32], const bf16_t* __restrict__ qptr, const bf16_t* __restrict__ kg, const bf16_t* __restrict__ vtg,
;               int ntiles, int q, float slope2, const float* __restrict__ cum2, float KN, bf16_t* smem) {
;     ...
;     bf16x8 qf[4];
; #pragma unroll
;     for (int ks = 0; ks < 4; ++ks) qf[ks] = *(const bf16x8*)(qptr + ks * 16 + h * 8);
;     float qn2 = 0.f;
; #pragma unroll
;     for (int ks = 0; ks < 4; ++ks)
; #pragma unroll
;         for (int j = 0; j < 8; ++j) { const float x = __uint_as_float(((unsigned)(unsigned short)qf[ks][j]) << 16); qn2 += x * x; }
;     qn2 = xsum32(qn2);
;     const float c1 = 0.125f * LOG2E;
;     const float sbound = sqrtf(qn2) * KN * c1 * 1.001f + 0.01f;
;     float m = -1e30f, l = 0.f;
; #pragma unroll
;     for (int dt = 0; dt < NDT; ++dt) O[dt] = zero16();
;     const float cq = FOX ? cum2[min(q, LT - 1)] : 0.f;
;     const int kend = FOX ? q + 1 : 16 + 64 * ((q + 48) >> 6);
;     const int wkend = __builtin_amdgcn_readfirstlane(FOX ? (q | 31) + 1 : 16 + 64 * (((q | 31) + 48) >> 6));
;     const int qlo = __builtin_amdgcn_readfirstlane(q & ~31);
;     constexpr int NVR = DV / 64;
;     u32x4 kr[2], vr[2][NVR];
;     ...
;     kr[0] = kr[1] = (u32x4){0u, 0u, 0u, 0u};
; #pragma unroll
;     for (int i = 0; i < NVR; ++i) vr[0][i] = vr[1][i] = (u32x4){0u, 0u, 0u, 0u};
;     LOAD_PAIR(ntiles - 1);
;     ...
;     l = xsum32(l);
;     const float inv = 1.0f / l;
; #pragma unroll
;     for (int dt = 0; dt < NDT; ++dt)
; #pragma unroll
;         for (int i = 0; i < 16; ++i) O[dt][i] *= inv;
.LBB0_640:
	v_mov_b32_e32 v0, v66
	s_nop 1
	v_permlane32_swap_b32_e32 v66, v0
	v_add_f32_e32 v0, v66, v0
	v_div_scale_f32 v66, s[4:5], v0, v0, 1.0
	v_rcp_f32_e32 v67, v66
	s_lshl_b32 s70, s91, 7
	v_readfirstlane_b32 s42, v154
	v_fma_f32 v68, -v66, v67, 1.0
	v_fmac_f32_e32 v67, v68, v67
	v_div_scale_f32 v68, vcc, 1.0, v0, 1.0
	v_mul_f32_e32 v69, v68, v67
	v_fma_f32 v70, -v66, v69, v68
	v_fmac_f32_e32 v69, v70, v67
	v_fma_f32 v66, -v66, v69, v68
	v_div_fmas_f32 v66, v66, v67, v69
	v_div_fixup_f32 v0, v66, v0, 1.0
	v_mul_f32_e64 v50, v50, v0
	v_mul_f32_e64 v51, v51, v0
	v_mul_f32_e64 v52, v52, v0
	v_mul_f32_e64 v53, v53, v0
	v_mul_f32_e64 v6, v6, v0
	v_mul_f32_e64 v7, v7, v0
	v_mul_f32_e64 v54, v54, v0
	v_mul_f32_e64 v55, v55, v0
	v_mul_f32_e64 v56, v56, v0
	v_mul_f32_e64 v57, v57, v0
	v_mul_f32_e64 v58, v58, v0
	v_mul_f32_e64 v59, v59, v0
	v_mul_f32_e64 v60, v60, v0
	v_mul_f32_e64 v61, v61, v0
	v_mul_f32_e64 v62, v62, v0
	v_mul_f32_e64 v63, v63, v0
	v_mul_f32_e64 v64, v64, v0
	v_mul_f32_e64 v65, v65, v0
	v_mul_f32_e64 v34, v34, v0
	v_mul_f32_e64 v35, v35, v0
	v_mul_f32_e64 v36, v36, v0
	v_mul_f32_e64 v37, v37, v0
	v_mul_f32_e64 v38, v38, v0
	v_mul_f32_e64 v39, v39, v0
	v_mul_f32_e64 v40, v40, v0
	v_mul_f32_e64 v41, v41, v0
	v_mul_f32_e64 v42, v42, v0
	v_mul_f32_e64 v43, v43, v0
	v_mul_f32_e64 v44, v44, v0
	v_mul_f32_e64 v45, v45, v0
	v_mul_f32_e64 v46, v46, v0
	v_mul_f32_e64 v47, v47, v0
	v_mul_f32_e64 v48, v48, v0
	v_mul_f32_e64 v49, v49, v0
	v_mul_f32_e64 v18, v18, v0
	v_mul_f32_e64 v19, v19, v0
	v_mul_f32_e64 v20, v20, v0
	v_mul_f32_e64 v21, v21, v0
	v_mul_f32_e64 v22, v22, v0
	v_mul_f32_e64 v23, v23, v0
	v_mul_f32_e64 v24, v24, v0
	v_mul_f32_e64 v25, v25, v0
	v_mul_f32_e64 v26, v26, v0
	v_mul_f32_e64 v27, v27, v0
	v_mul_f32_e64 v28, v28, v0
	v_mul_f32_e64 v29, v29, v0
	v_mul_f32_e64 v30, v30, v0
	v_mul_f32_e64 v31, v31, v0
	v_mul_f32_e64 v32, v32, v0
	v_mul_f32_e64 v33, v33, v0
	v_mul_f32_e64 v2, v2, v0
	v_mul_f32_e64 v3, v3, v0
	v_mul_f32_e64 v4, v4, v0
	v_mul_f32_e64 v5, v5, v0
	v_mul_f32_e64 v8, v8, v0
	v_mul_f32_e64 v9, v9, v0
	v_mul_f32_e64 v10, v10, v0
	v_mul_f32_e64 v11, v11, v0
	v_mul_f32_e64 v12, v12, v0
	v_mul_f32_e64 v13, v13, v0
	v_mul_f32_e64 v14, v14, v0
	v_mul_f32_e64 v15, v15, v0
	v_mul_f32_e64 v16, v16, v0
	v_mul_f32_e64 v17, v17, v0
	global_store_dwordx4 v[146:147], v[50:53], off
	global_store_dwordx4 v[146:147], v[54:57], off offset:16
	global_store_dwordx4 v[146:147], v[58:61], off offset:32
	global_store_dwordx4 v[146:147], v[62:65], off offset:48
	global_store_dwordx4 v[146:147], v[34:37], off offset:64
	global_store_dwordx4 v[146:147], v[38:41], off offset:80
	global_store_dwordx4 v[146:147], v[42:45], off offset:96
	global_store_dwordx4 v[146:147], v[46:49], off offset:112
	global_store_dwordx4 v[146:147], v[18:21], off offset:128
	global_store_dwordx4 v[146:147], v[22:25], off offset:144
	global_store_dwordx4 v[146:147], v[26:29], off offset:160
	global_store_dwordx4 v[146:147], v[30:33], off offset:176
	global_store_dwordx4 v[146:147], v[2:5], off offset:192
	global_store_dwordx4 v[146:147], v[6:9], off offset:208
	global_store_dwordx4 v[146:147], v[10:13], off offset:224
	global_store_dwordx4 v[146:147], v[14:17], off offset:240
	v_mov_b32_e32 v7, v210
	global_load_dword v8, v1, s[68:69] offset:4
	s_andn2_b64 vcc, exec, s[52:53]
	v_bfe_u32 v6, v7, 5, 1
	v_lshlrev_b32_e32 v0, 4, v6
	v_lshl_add_u64 v[2:3], v[166:167], 0, v[0:1]
	global_load_dwordx4 v[100:103], v[2:3], off offset:128
	global_load_dwordx4 v[104:107], v[2:3], off offset:160
	global_load_dwordx4 v[108:111], v[2:3], off offset:192
	global_load_dwordx4 v[112:115], v[2:3], off offset:224
	v_ashrrev_i32_e32 v166, 3, v7
	v_ashrrev_i32_e32 v167, 31, v166
	s_waitcnt vmcnt(3)
	v_and_b32_e32 v2, 0xffff0000, v100
	v_lshlrev_b32_e32 v0, 16, v100
	v_mul_f32_e32 v9, v2, v2
	v_lshlrev_b32_e32 v3, 16, v101
	v_fmac_f32_e32 v9, v0, v0
	v_and_b32_e32 v4, 0xffff0000, v101
	v_fmac_f32_e32 v9, v3, v3
	v_lshlrev_b32_e32 v5, 16, v102
	v_fmac_f32_e32 v9, v4, v4
	v_and_b32_e32 v10, 0xffff0000, v102
	v_fmac_f32_e32 v9, v5, v5
	v_lshlrev_b32_e32 v11, 16, v103
	v_fmac_f32_e32 v9, v10, v10
	v_and_b32_e32 v12, 0xffff0000, v103
	v_fmac_f32_e32 v9, v11, v11
	s_waitcnt vmcnt(2)
	v_lshlrev_b32_e32 v13, 16, v104
	v_fmac_f32_e32 v9, v12, v12
	v_and_b32_e32 v14, 0xffff0000, v104
	v_fmac_f32_e32 v9, v13, v13
	v_lshlrev_b32_e32 v15, 16, v105
	v_fmac_f32_e32 v9, v14, v14
	v_and_b32_e32 v16, 0xffff0000, v105
	v_fmac_f32_e32 v9, v15, v15
	v_lshlrev_b32_e32 v17, 16, v106
	v_fmac_f32_e32 v9, v16, v16
	v_and_b32_e32 v18, 0xffff0000, v106
	v_fmac_f32_e32 v9, v17, v17
	v_lshlrev_b32_e32 v19, 16, v107
	v_fmac_f32_e32 v9, v18, v18
	v_and_b32_e32 v20, 0xffff0000, v107
	v_fmac_f32_e32 v9, v19, v19
	s_waitcnt vmcnt(1)
	v_lshlrev_b32_e32 v21, 16, v108
	v_fmac_f32_e32 v9, v20, v20
	v_and_b32_e32 v22, 0xffff0000, v108
	v_fmac_f32_e32 v9, v21, v21
	v_lshlrev_b32_e32 v23, 16, v109
	v_fmac_f32_e32 v9, v22, v22
	v_and_b32_e32 v24, 0xffff0000, v109
	v_fmac_f32_e32 v9, v23, v23
	v_lshlrev_b32_e32 v25, 16, v110
	v_fmac_f32_e32 v9, v24, v24
	v_and_b32_e32 v26, 0xffff0000, v110
	v_fmac_f32_e32 v9, v25, v25
	v_lshlrev_b32_e32 v27, 16, v111
	v_fmac_f32_e32 v9, v26, v26
	v_and_b32_e32 v28, 0xffff0000, v111
	v_fmac_f32_e32 v9, v27, v27
	s_waitcnt vmcnt(0)
	v_lshlrev_b32_e32 v29, 16, v112
	v_fmac_f32_e32 v9, v28, v28
	v_and_b32_e32 v30, 0xffff0000, v112
	v_fmac_f32_e32 v9, v29, v29
	v_lshlrev_b32_e32 v31, 16, v113
	v_fmac_f32_e32 v9, v30, v30
	v_fmac_f32_e32 v9, v31, v31
	v_and_b32_e32 v0, 0xffff0000, v113
	v_fmac_f32_e32 v9, v0, v0
	v_lshlrev_b32_e32 v0, 16, v114
	v_fmac_f32_e32 v9, v0, v0
	v_and_b32_e32 v0, 0xffff0000, v114
	v_fmac_f32_e32 v9, v0, v0
	v_lshlrev_b32_e32 v0, 16, v115
	v_fmac_f32_e32 v9, v0, v0
	v_and_b32_e32 v0, 0xffff0000, v115
	v_fmac_f32_e32 v9, v0, v0
	v_lshlrev_b32_e32 v0, 3, v7
	v_and_b32_e32 v0, 56, v0
	v_mov_b32_e32 v10, v9
	v_lshlrev_b32_e32 v0, 1, v0
	s_nop 0
	v_permlane32_swap_b32_e32 v9, v10
	v_lshl_add_u64 v[168:169], s[50:51], 0, v[0:1]
	v_lshl_add_u64 v[2:3], s[14:15], 0, v[0:1]
	v_lshlrev_b64 v[4:5], 7, v[166:167]
	s_cbranch_vccnz .LBB0_643
	s_add_i32 s20, s47, -1
	v_lshl_add_u32 v11, s20, 6, v166
	v_min_i32_e32 v12, 0x200f, v11
	v_ashrrev_i32_e32 v13, 31, v12
	s_lshl_b64 s[4:5], s[20:21], 19
	v_lshlrev_b64 v[12:13], 12, v[12:13]
	v_lshl_add_u64 v[14:15], v[2:3], 0, s[4:5]
	v_lshl_add_u64 v[12:13], v[168:169], 0, v[12:13]
	v_lshl_add_u64 v[14:15], v[14:15], 0, v[4:5]
	global_load_dwordx4 v[116:119], v[12:13], off offset:1152
	global_load_dwordx4 v[120:123], v[14:15], off
	v_add_co_u32_e32 v12, vcc, 0x2000, v14
	s_nop 1
	v_addc_co_u32_e32 v13, vcc, 0, v15, vcc
	global_load_dwordx4 v[124:127], v[12:13], off
	s_andn2_b64 vcc, exec, s[60:61]
	s_cbranch_vccnz .LBB0_644

; DI f32x16 zero16() { f32x16 z; for (int i = 0; i < 16; ++i) z[i] = 0.f; return z; }
; template <int DV, bool FOX>
; DI void flash(f32x16 (&O)[DV / 32], const bf16_t* __restrict__ qptr, const bf16_t* __restrict__ kg, const bf16_t* __restrict__ vtg,
;               int ntiles, int q, float slope2, const float* __restrict__ cum2, float KN, bf16_t* smem) {
;     ...
;         const int kt = kt0 - pj;
;         if (kt < 0) break;
;         const bf16_t* Ks = smem + (cur * 2 + pj) * BUF; const bf16_t* Vs = Ks + KS_ELEMS;
;         const int kb = kt * 64;
;         const float cklast = pj ? ckl1 : ckl0;
;         if (kb < wkend && !wskip) {
;         f32x16 s[2];
; #pragma unroll
;         for (int sub = 0; sub < 2; ++sub) {
;             s[sub] = zero16();
; #pragma unroll
;             for (int ks = 0; ks < 4; ++ks) {
;                 const bf16x8 a = *(const bf16x8*)(Ks + (sub * 32 + pr) * 72 + ks * 16 + h * 8);
;                 s[sub] = mfma32(a, qf[ks], s[sub]);
;             }
;         }
;         float mx = -INFINITY;
;         if (kb + 63 < qlo) {
; #pragma unroll
;             for (int sub = 0; sub < 2; ++sub) {
; #pragma unroll
;                 for (int i8 = 0; i8 < 2; ++i8) {
;                     const int k0 = kb + sub * 32 + 16 * i8 + 8 * h;
;                     float ck[8];
;                     float base = 0.f;
;                     if (FOX) {
;                         const f32x4 c0 = *(const f32x4*)(cum2 + k0), c1v = *(const f32x4*)(cum2 + k0 + 4);
;                         ck[0] = c0[0]; ck[1] = c0[1]; ck[2] = c0[2]; ck[3] = c0[3]; ck[4] = c1v[0]; ck[5] = c1v[1]; ck[6] = c1v[2]; ck[7] = c1v[3];
;                     } else base = -slope2 * (float)(q - k0);
; #pragma unroll
;                     for (int e = 0; e < 8; ++e) {
;                         const float bias = FOX ? cq - ck[e] : fmaf(slope2, (float)e, base);
;                         const float t = fmaf(s[sub][8 * i8 + e], c1, bias);
;                         s[sub][8 * i8 + e] = t;
;                         mx = fmaxf(mx, t);
;                     }
;                 }
;             }
;         } else {
; #pragma unroll
;             for (int sub = 0; sub < 2; ++sub) {
; #pragma unroll
;                 for (int i8 = 0; i8 < 2; ++i8) {
;                     const int k0 = kb + sub * 32 + 16 * i8 + 8 * h;
;                     float ck[8];
;                     if (FOX) {
.LBB0_653:
	s_sub_i32 s52, s42, s67
	s_cmp_gt_i32 s52, -1
	s_cselect_b64 s[50:51], -1, 0
	s_cmp_lt_i32 s52, 0
	s_cbranch_scc1 .LBB0_662
	s_lshl_b32 s68, s52, 6
	s_cmp_gt_i32 s68, s61
	s_cselect_b64 s[52:53], -1, 0
	s_or_b64 s[52:53], s[52:53], s[10:11]
	s_and_b64 vcc, exec, s[52:53]
	s_cbranch_vccnz .LBB0_663
	s_or_b32 s52, s67, s43
	s_mulk_i32 s52, 0x6c00
	v_add_u32_e32 v142, s52, v224
	v_add_u32_e32 v151, v142, v219
	ds_read_b128 v[68:71], v151
	ds_read_b128 v[72:75], v151 offset:32
	s_or_b32 s69, s68, 63
	s_mov_b64 s[52:53], -1
	s_cmp_lt_i32 s69, s60
	s_waitcnt lgkmcnt(1)
	v_mfma_f32_32x32x16_bf16 v[84:99], v[68:71], v[100:103], 0
	s_waitcnt lgkmcnt(0)
	v_mfma_f32_32x32x16_bf16 v[84:99], v[72:75], v[104:107], v[84:99]
	ds_read_b128 v[68:71], v151 offset:64
	ds_read_b128 v[72:75], v151 offset:96
	s_waitcnt lgkmcnt(1)
	v_mfma_f32_32x32x16_bf16 v[84:99], v[68:71], v[108:111], v[84:99]
	ds_read_b128 v[68:71], v151 offset:4608
	ds_read_b128 v[176:179], v151 offset:4640
	s_waitcnt lgkmcnt(2)
	v_mfma_f32_32x32x16_bf16 v[84:99], v[72:75], v[112:115], v[84:99]
	s_waitcnt lgkmcnt(1)
	v_mfma_f32_32x32x16_bf16 v[68:83], v[68:71], v[100:103], 0
	s_waitcnt lgkmcnt(0)
	v_mfma_f32_32x32x16_bf16 v[68:83], v[176:179], v[104:107], v[68:83]
	ds_read_b128 v[176:179], v151 offset:4672
	ds_read_b128 v[226:229], v151 offset:4704
	s_waitcnt lgkmcnt(1)
	v_mfma_f32_32x32x16_bf16 v[68:83], v[176:179], v[108:111], v[68:83]
	s_waitcnt lgkmcnt(0)
	v_mfma_f32_32x32x16_bf16 v[68:83], v[226:229], v[112:115], v[68:83]
	s_cbranch_scc1 .LBB0_657
	v_or_b32_e32 v171, s68, v167
	v_or_b32_e32 v151, 1, v171
	v_sub_u32_e32 v158, v154, v171
	v_sub_u32_e32 v176, v145, v151
	v_cvt_f32_i32_e32 v158, v158
	v_cvt_f32_i32_e32 v177, v176
	v_cmp_lt_i32_e32 vcc, v151, v67
	v_or_b32_e32 v151, 3, v171
	v_and_b32_e32 v176, 0x7fffffff, v158
	v_or_b32_e32 v158, 2, v171
	v_and_b32_e32 v177, 0x7fffffff, v177
	v_sub_u32_e32 v178, v145, v151
	v_sub_u32_e32 v179, v154, v158
	v_mul_f32_e64 v176, v174, v176
	v_mul_f32_e64 v177, v175, v177
	v_cvt_f32_i32_e32 v180, v179
	v_cvt_f32_i32_e32 v178, v178
	v_fma_f32 v176, v84, s24, -v176
	v_fma_f32 v177, v85, s24, -v177
	v_or_b32_e32 v182, 4, v171
	v_cndmask_b32_e32 v177, v216, v177, vcc
	v_cmp_lt_i32_e32 vcc, v171, v162
	v_and_b32_e32 v179, 0x7fffffff, v178
	v_and_b32_e32 v178, 0x7fffffff, v180
	v_cndmask_b32_e32 v176, v216, v176, vcc
	v_cmp_lt_i32_e32 vcc, v151, v67
	v_or_b32_e32 v151, 5, v171
	v_sub_u32_e32 v180, v145, v151
	v_sub_u32_e32 v183, v154, v182
	v_mul_f32_e64 v178, v174, v178
	v_mul_f32_e64 v179, v175, v179
	v_cvt_f32_i32_e32 v183, v183
	v_cvt_f32_i32_e32 v180, v180
	v_fma_f32 v178, v86, s24, -v178
	v_fma_f32 v179, v87, s24, -v179
	v_max3_f32 v181, v176, s89, v177
	v_cndmask_b32_e32 v179, v216, v179, vcc
	v_cmp_lt_i32_e32 vcc, v158, v162
	v_or_b32_e32 v184, 6, v171
	v_sub_u32_e32 v185, v154, v184
	v_cndmask_b32_e32 v178, v216, v178, vcc
	v_cmp_lt_i32_e32 vcc, v151, v67
	v_or_b32_e32 v151, 7, v171
	v_max3_f32 v158, v181, v178, v179
	v_and_b32_e32 v181, 0x7fffffff, v180
	v_and_b32_e32 v180, 0x7fffffff, v183
	v_sub_u32_e32 v183, v145, v151
	v_mul_f32_e64 v180, v174, v180
	v_mul_f32_e64 v181, v175, v181
	v_cvt_f32_i32_e32 v185, v185
	v_cvt_f32_i32_e32 v183, v183
	v_fma_f32 v180, v88, s24, -v180
	v_fma_f32 v181, v89, s24, -v181
	v_or_b32_e32 v188, 18, v171
	v_cndmask_b32_e32 v181, v216, v181, vcc
	v_cmp_lt_i32_e32 vcc, v182, v162
	v_and_b32_e32 v183, 0x7fffffff, v183
	v_and_b32_e32 v182, 0x7fffffff, v185
	v_cndmask_b32_e32 v180, v216, v180, vcc
	v_cmp_lt_i32_e32 vcc, v151, v67
	v_or_b32_e32 v151, 17, v171
	v_sub_u32_e32 v185, v164, v171
	v_sub_u32_e32 v186, v161, v151
	v_mul_f32_e64 v182, v174, v182
	v_mul_f32_e64 v183, v175, v183
	v_cvt_f32_i32_e32 v186, v186
	v_cvt_f32_i32_e32 v185, v185
	v_fma_f32 v182, v90, s24, -v182
	v_fma_f32 v183, v91, s24, -v183
	v_sub_u32_e32 v187, v154, v188
	v_cndmask_b32_e32 v183, v216, v183, vcc
	v_cmp_lt_i32_e32 vcc, v184, v162
	v_and_b32_e32 v184, 0x7fffffff, v185
	v_and_b32_e32 v185, 0x7fffffff, v186
	v_cndmask_b32_e32 v182, v216, v182, vcc
	v_cmp_lt_i32_e32 vcc, v151, v155
	v_or_b32_e32 v151, 19, v171
	v_sub_u32_e32 v186, v145, v151
	v_mul_f32_e64 v184, v174, v184
	v_mul_f32_e64 v185, v175, v185
	v_cvt_f32_i32_e32 v189, v187
	v_cvt_f32_i32_e32 v186, v186
	v_fma_f32 v184, v92, s24, -v184
	v_fma_f32 v185, v93, s24, -v185
	v_or_b32_e32 v190, 20, v171
	v_cndmask_b32_e32 v185, v216, v185, vcc
	v_cmp_lt_i32_e32 vcc, v171, v160
	v_and_b32_e32 v187, 0x7fffffff, v186
	v_and_b32_e32 v186, 0x7fffffff, v189
	v_cndmask_b32_e32 v184, v216, v184, vcc
	v_cmp_lt_i32_e32 vcc, v151, v67
	v_or_b32_e32 v151, 21, v171
	v_sub_u32_e32 v189, v145, v151
	v_sub_u32_e32 v191, v154, v190
	v_cvt_f32_i32_e32 v191, v191
	v_cvt_f32_i32_e32 v189, v189
	v_mul_f32_e64 v186, v174, v186
	v_mul_f32_e64 v187, v175, v187
	v_or_b32_e32 v192, 22, v171
	v_fma_f32 v186, v94, s24, -v186
	v_fma_f32 v187, v95, s24, -v187
	v_and_b32_e32 v189, 0x7fffffff, v189
	v_cndmask_b32_e32 v187, v216, v187, vcc
	v_cmp_lt_i32_e32 vcc, v188, v162
	v_and_b32_e32 v188, 0x7fffffff, v191
	v_sub_u32_e32 v193, v154, v192
	v_cndmask_b32_e32 v186, v216, v186, vcc
	v_cmp_lt_i32_e32 vcc, v151, v67
	v_or_b32_e32 v151, 23, v171
	v_mul_f32_e64 v188, v174, v188
	v_mul_f32_e64 v189, v175, v189
	v_sub_u32_e32 v191, v145, v151
	v_cvt_f32_i32_e32 v193, v193
	v_fma_f32 v188, v96, s24, -v188
	v_fma_f32 v189, v97, s24, -v189
	v_cvt_f32_i32_e32 v191, v191
	v_cndmask_b32_e32 v189, v216, v189, vcc
	v_cmp_lt_i32_e32 vcc, v190, v162
	v_or_b32_e32 v194, 32, v171
	v_and_b32_e32 v190, 0x7fffffff, v193
	v_cndmask_b32_e32 v188, v216, v188, vcc
	v_cmp_lt_i32_e32 vcc, v151, v67
	v_or_b32_e32 v151, 33, v171
; template <int DV, bool FOX>
; DI void flash(f32x16 (&O)[DV / 32], const bf16_t* __restrict__ qptr, const bf16_t* __restrict__ kg, const bf16_t* __restrict__ vtg,
;               int ntiles, int q, float slope2, const float* __restrict__ cum2, float KN, bf16_t* smem) {
;     ...
;         } else {
; #pragma unroll
;             for (int sub = 0; sub < 2; ++sub) {
; #pragma unroll
;                 for (int i8 = 0; i8 < 2; ++i8) {
;                     const int k0 = kb + sub * 32 + 16 * i8 + 8 * h;
;                     float ck[8];
;                     if (FOX) {
;                         const f32x4 c0 = *(const f32x4*)(cum2 + k0), c1v = *(const f32x4*)(cum2 + k0 + 4);
;                         ck[0] = c0[0]; ck[1] = c0[1]; ck[2] = c0[2]; ck[3] = c0[3]; ck[4] = c1v[0]; ck[5] = c1v[1]; ck[6] = c1v[2]; ck[7] = c1v[3];
;                     }
; #pragma unroll
;                     for (int e = 0; e < 8; ++e) {
;                         const int k = k0 + e;
;                         float t = s[sub][8 * i8 + e] * c1;
;                         if (FOX) t += cq - ck[e];
;                         else t -= slope2 * fabsf((float)(q - k));
;                         t = (k < kend) ? t : -INFINITY;
;                         s[sub][8 * i8 + e] = t;
;                         mx = fmaxf(mx, t);
;                     }
;                 }
;             }
	v_sub_u32_e32 v193, v145, v151
	v_sub_u32_e32 v195, v154, v194
	v_and_b32_e32 v191, 0x7fffffff, v191
	v_cvt_f32_i32_e32 v195, v195
	v_cvt_f32_i32_e32 v193, v193
	v_mul_f32_e64 v190, v174, v190
	v_mul_f32_e64 v191, v175, v191
	v_or_b32_e32 v196, 34, v171
	v_fma_f32 v190, v98, s24, -v190
	v_fma_f32 v191, v99, s24, -v191
	v_and_b32_e32 v193, 0x7fffffff, v193
	v_cndmask_b32_e32 v191, v216, v191, vcc
	v_cmp_lt_i32_e32 vcc, v192, v162
	v_and_b32_e32 v192, 0x7fffffff, v195
	v_sub_u32_e32 v197, v154, v196
	v_cndmask_b32_e32 v190, v216, v190, vcc
	v_cmp_lt_i32_e32 vcc, v151, v67
	v_or_b32_e32 v151, 35, v171
	v_mul_f32_e64 v192, v174, v192
	v_mul_f32_e64 v193, v175, v193
	v_sub_u32_e32 v195, v145, v151
	v_cvt_f32_i32_e32 v197, v197
	v_fma_f32 v192, v68, s24, -v192
	v_fma_f32 v193, v69, s24, -v193
	v_cvt_f32_i32_e32 v195, v195
	v_cndmask_b32_e32 v193, v216, v193, vcc
	v_cmp_lt_i32_e32 vcc, v194, v162
	v_or_b32_e32 v198, 36, v171
	v_and_b32_e32 v194, 0x7fffffff, v197
	v_cndmask_b32_e32 v192, v216, v192, vcc
	v_cmp_lt_i32_e32 vcc, v151, v67
	v_or_b32_e32 v151, 37, v171
	v_sub_u32_e32 v197, v145, v151
	v_sub_u32_e32 v199, v154, v198
	v_and_b32_e32 v195, 0x7fffffff, v195
	v_cvt_f32_i32_e32 v199, v199
	v_cvt_f32_i32_e32 v197, v197
	v_max3_f32 v158, v158, v180, v181
	v_mul_f32_e64 v194, v174, v194
	v_mul_f32_e64 v195, v175, v195
	v_max3_f32 v158, v158, v182, v183
	v_fma_f32 v194, v70, s24, -v194
	v_fma_f32 v195, v71, s24, -v195
	v_max3_f32 v158, v158, v184, v185
	v_cndmask_b32_e32 v195, v216, v195, vcc
	v_cmp_lt_i32_e32 vcc, v196, v162
	v_or_b32_e32 v206, 38, v171
	v_max3_f32 v158, v158, v186, v187
	v_cndmask_b32_e32 v194, v216, v194, vcc
	v_and_b32_e32 v197, 0x7fffffff, v197
	v_and_b32_e32 v196, 0x7fffffff, v199
	v_cmp_lt_i32_e32 vcc, v151, v67
	v_or_b32_e32 v205, 39, v171
	v_sub_u32_e32 v151, v154, v206
	v_max3_f32 v158, v158, v188, v189
	v_mul_f32_e64 v196, v174, v196
	v_mul_f32_e64 v197, v175, v197
	v_cvt_f32_i32_e32 v151, v151
	v_sub_u32_e32 v199, v154, v205
	v_max3_f32 v158, v158, v190, v191
	v_fma_f32 v196, v72, s24, -v196
	v_fma_f32 v197, v73, s24, -v197
	v_cvt_f32_i32_e32 v202, v199
	v_max3_f32 v158, v158, v192, v193
	v_cndmask_b32_e32 v197, v216, v197, vcc
	v_cmp_lt_i32_e32 vcc, v198, v162
	v_max3_f32 v158, v158, v194, v195
	v_and_b32_e32 v151, 0x7fffffff, v151
	v_cndmask_b32_e32 v196, v216, v196, vcc
	v_max3_f32 v204, v158, v196, v197
	v_mov_b32_e32 v158, v74
	v_mov_b32_e32 v198, v75
	v_mov_b32_e32 v199, v159
	v_mul_f32_e64 v200, v158, v150
	v_mul_f32_e64 v201, v159, v151
	v_and_b32_e32 v151, 0x7fffffff, v202
	v_mul_f32_e64 v198, v198, v150
	v_mul_f32_e64 v199, v199, v151
	v_mov_b32_e32 v202, v200
	v_mov_b32_e32 v203, v198
	v_mov_b32_e32 v198, v201
	v_add_f32_e64 v198, v202, -v198
	v_add_f32_e64 v199, v203, -v199
	v_cmp_lt_i32_e32 vcc, v205, v67
	v_or_b32_e32 v226, 48, v171
	v_or_b32_e32 v207, 49, v171
	v_cndmask_b32_e32 v199, v216, v199, vcc
	v_cmp_lt_i32_e32 vcc, v206, v162
	v_sub_u32_e32 v151, v154, v226
	v_cvt_f32_i32_e32 v151, v151
	v_cndmask_b32_e32 v198, v216, v198, vcc
	v_sub_u32_e32 v201, v154, v207
	v_max3_f32 v206, v204, v198, v199
	v_cvt_f32_i32_e32 v204, v201
	v_mov_b32_e32 v158, v76
	v_and_b32_e32 v151, 0x7fffffff, v151
	v_mov_b32_e32 v200, v77
	v_mov_b32_e32 v201, v159
	v_mul_f32_e64 v202, v158, v150
	v_mul_f32_e64 v203, v159, v151
	v_and_b32_e32 v151, 0x7fffffff, v204
	v_mul_f32_e64 v200, v200, v150
	v_mul_f32_e64 v201, v201, v151
	v_mov_b32_e32 v204, v202
	v_mov_b32_e32 v205, v200
	v_mov_b32_e32 v200, v203
	v_add_f32_e64 v200, v204, -v200
	v_add_f32_e64 v201, v205, -v201
	v_cmp_lt_i32_e32 vcc, v207, v67
	v_or_b32_e32 v228, 50, v171
	v_or_b32_e32 v227, 51, v171
	v_cndmask_b32_e32 v203, v216, v201, vcc
	v_cmp_lt_i32_e32 vcc, v226, v162
	v_sub_u32_e32 v151, v154, v228
	v_cvt_f32_i32_e32 v151, v151
	v_cndmask_b32_e32 v202, v216, v200, vcc
	v_sub_u32_e32 v201, v154, v227
	v_max3_f32 v226, v206, v202, v203
	v_cvt_f32_i32_e32 v206, v201
	v_mov_b32_e32 v158, v78
	v_and_b32_e32 v151, 0x7fffffff, v151
	v_mov_b32_e32 v200, v79
	v_mov_b32_e32 v201, v159
	v_mul_f32_e64 v204, v158, v150
	v_mul_f32_e64 v205, v159, v151
	v_and_b32_e32 v151, 0x7fffffff, v206
	v_mul_f32_e64 v200, v200, v150
	v_mul_f32_e64 v201, v201, v151
	v_mov_b32_e32 v206, v204
	v_mov_b32_e32 v207, v200
	v_mov_b32_e32 v200, v205
	v_add_f32_e64 v200, v206, -v200
	v_add_f32_e64 v201, v207, -v201
	v_cmp_lt_i32_e32 vcc, v227, v67
	v_or_b32_e32 v230, 52, v171
	v_or_b32_e32 v229, 53, v171
	v_cndmask_b32_e32 v201, v216, v201, vcc
	v_cmp_lt_i32_e32 vcc, v228, v162
	v_sub_u32_e32 v151, v154, v230
	v_cvt_f32_i32_e32 v151, v151
	v_cndmask_b32_e32 v200, v216, v200, vcc
	v_sub_u32_e32 v205, v154, v229
	v_max3_f32 v228, v226, v200, v201
	v_cvt_f32_i32_e32 v226, v205
	v_mov_b32_e32 v158, v80
	v_and_b32_e32 v151, 0x7fffffff, v151
	v_mov_b32_e32 v204, v81
	v_mov_b32_e32 v205, v159
	v_mul_f32_e64 v206, v158, v150
	v_mul_f32_e64 v207, v159, v151
	v_and_b32_e32 v151, 0x7fffffff, v226
	v_mul_f32_e64 v204, v204, v150
	v_mul_f32_e64 v205, v205, v151
	v_mov_b32_e32 v226, v206
	v_mov_b32_e32 v227, v204
	v_mov_b32_e32 v204, v207
	v_add_f32_e64 v204, v226, -v204
	v_add_f32_e64 v205, v227, -v205
	v_cmp_lt_i32_e32 vcc, v229, v67
	v_or_b32_e32 v231, 55, v171
	v_or_b32_e32 v171, 54, v171
	v_cndmask_b32_e32 v205, v216, v205, vcc
	v_cmp_lt_i32_e32 vcc, v230, v162
	v_sub_u32_e32 v151, v154, v171
	v_cvt_f32_i32_e32 v151, v151
	v_cndmask_b32_e32 v204, v216, v204, vcc
	v_sub_u32_e32 v207, v154, v231
	v_max3_f32 v230, v228, v204, v205
	v_cvt_f32_i32_e32 v228, v207
	v_mov_b32_e32 v158, v82
	v_and_b32_e32 v151, 0x7fffffff, v151
	v_mov_b32_e32 v206, v83
	v_mov_b32_e32 v207, v159
	v_mul_f32_e64 v226, v158, v150
	v_mul_f32_e64 v227, v159, v151
	v_and_b32_e32 v151, 0x7fffffff, v228
	v_mul_f32_e64 v206, v206, v150
	v_mul_f32_e64 v207, v207, v151
	v_mov_b32_e32 v228, v226
	v_mov_b32_e32 v229, v206
	v_mov_b32_e32 v206, v227
	v_add_f32_e64 v206, v228, -v206
	v_add_f32_e64 v207, v229, -v207
	v_cmp_lt_i32_e32 vcc, v231, v67
	s_mov_b64 s[52:53], 0
	s_nop 0
	v_cndmask_b32_e32 v207, v216, v207, vcc
	v_cmp_lt_i32_e32 vcc, v171, v162
	s_nop 1
	v_cndmask_b32_e32 v206, v216, v206, vcc
	v_max3_f32 v151, v230, v206, v207
; DI float ex2(float x) { return __builtin_amdgcn_exp2f(x); }
; DI float xmax32(float x) { auto r = __builtin_amdgcn_permlane32_swap(__float_as_uint(x), __float_as_uint(x), false, false); return fmaxf(__uint_as_float(r[0]), __uint_as_float(r[1])); }
; template <int DV, bool FOX>
; DI void flash(f32x16 (&O)[DV / 32], const bf16_t* __restrict__ qptr, const bf16_t* __restrict__ kg, const bf16_t* __restrict__ vtg,
;               int ntiles, int q, float slope2, const float* __restrict__ cum2, float KN, bf16_t* smem) {
;     ...
;                     } else base = -slope2 * (float)(q - k0);
; #pragma unroll
;                     for (int e = 0; e < 8; ++e) {
;                         const float bias = FOX ? cq - ck[e] : fmaf(slope2, (float)e, base);
;                         const float t = fmaf(s[sub][8 * i8 + e], c1, bias);
;                         s[sub][8 * i8 + e] = t;
;                         mx = fmaxf(mx, t);
;                     }
;                 }
;     ...
;         mx = xmax32(mx);
;         const float mn = fmaxf(m, mx);
;         if (__any(mn > m)) {
;             const float alpha = ex2(m - mn);
;             l *= alpha;
; #pragma unroll
;             for (int dt = 0; dt < NDT; ++dt)
; #pragma unroll
;                 for (int i = 0; i < 16; ++i) O[dt][i] *= alpha;
;         }
.LBB0_657:
	s_andn2_b64 vcc, exec, s[52:53]
	s_cbranch_vccnz .LBB0_659
	v_subrev_u32_e32 v151, s68, v154
	v_add_u32_e32 v158, v151, v209
	v_cvt_f32_i32_e32 v171, v158
	v_mul_f32_e64 v158, -v159, v171
	v_fma_f32 v177, -v159, v171, v159
	v_fma_f32 v176, 0, v159, v158
	v_fma_f32 v178, v174, s26, v158
	v_fma_f32 v179, v175, s27, v158
	v_fma_f32 v176, v84, s24, v176
	v_fma_f32 v177, v85, s24, v177
	v_fma_f32 v178, v86, s24, v178
	v_fma_f32 v179, v87, s24, v179
	v_max3_f32 v84, v176, s89, v177
	v_max3_f32 v86, v84, v178, v179
	v_fma_f32 v84, v174, s28, v158
	v_fma_f32 v85, v175, s29, v158
	s_nop 0
	v_fma_f32 v180, v88, s24, v84
	v_fma_f32 v181, v89, s24, v85
	v_add_u32_e32 v84, v220, v151
	v_cvt_f32_i32_e32 v87, v84
	v_fma_f32 v84, v174, s48, v158
	v_fma_f32 v85, v175, s49, v158
	v_max3_f32 v86, v86, v180, v181
	v_fma_f32 v182, v90, s24, v84
	v_fma_f32 v183, v91, s24, v85
	v_mul_f32_e64 v84, -v159, v87
	v_max3_f32 v85, v86, v182, v183
	v_fma_f32 v86, 0, v159, v84
	v_fma_f32 v87, -v159, v87, v159
	v_fma_f32 v184, v92, s24, v86
	v_fma_f32 v185, v93, s24, v87
	s_nop 0
	v_max3_f32 v85, v85, v184, v185
	v_fma_f32 v86, v174, s26, v84
	v_fma_f32 v87, v175, s27, v84
	s_nop 0
	v_fma_f32 v186, v94, s24, v86
	v_fma_f32 v187, v95, s24, v87
	s_nop 0
	v_max3_f32 v85, v85, v186, v187
	v_fma_f32 v86, v174, s28, v84
	v_fma_f32 v87, v175, s29, v84
	s_nop 0
	v_fma_f32 v188, v96, s24, v86
	v_fma_f32 v189, v97, s24, v87
	s_nop 0
	v_max3_f32 v86, v85, v188, v189
	v_add_u32_e32 v85, v221, v151
	v_cvt_f32_i32_e32 v87, v85
	v_fma_f32 v85, v175, s49, v84
	v_fma_f32 v84, v174, s48, v84
	s_nop 0
	v_fma_f32 v190, v98, s24, v84
	v_fma_f32 v191, v99, s24, v85
	v_mul_f32_e64 v84, -v159, v87
	v_max3_f32 v85, v86, v190, v191
	v_fma_f32 v86, 0, v159, v84
	v_fma_f32 v87, -v159, v87, v159
	v_fma_f32 v192, v68, s24, v86
	v_fma_f32 v193, v69, s24, v87
	s_nop 0
	v_max3_f32 v85, v85, v192, v193
	v_fma_f32 v68, v174, s26, v84
	v_fma_f32 v69, v175, s27, v84
	s_nop 0
	v_fma_f32 v194, v70, s24, v68
	v_fma_f32 v195, v71, s24, v69
	v_fma_f32 v68, v174, s28, v84
	v_fma_f32 v69, v175, s29, v84
	v_max3_f32 v70, v85, v194, v195
	v_fma_f32 v196, v72, s24, v68
	v_fma_f32 v197, v73, s24, v69
	v_add_u32_e32 v68, v222, v151
	v_cvt_f32_i32_e32 v71, v68
	v_fma_f32 v68, v174, s48, v84
	v_fma_f32 v69, v175, s49, v84
	v_max3_f32 v70, v70, v196, v197
	v_fma_f32 v198, v74, s24, v68
	v_fma_f32 v199, v75, s24, v69
	v_mul_f32_e64 v68, -v159, v71
	v_max3_f32 v69, v70, v198, v199
	v_fma_f32 v70, 0, v159, v68
	v_fma_f32 v71, -v159, v71, v159
	v_fma_f32 v202, v76, s24, v70
	v_fma_f32 v203, v77, s24, v71
	s_nop 0
	v_max3_f32 v69, v69, v202, v203
	v_fma_f32 v70, v174, s26, v68
	v_fma_f32 v71, v175, s27, v68
	s_nop 0
	v_fma_f32 v200, v78, s24, v70
	v_fma_f32 v201, v79, s24, v71
	s_nop 0
	v_max3_f32 v69, v69, v200, v201
	v_fma_f32 v70, v174, s28, v68
	v_fma_f32 v71, v175, s29, v68
	s_nop 0
	v_fma_f32 v204, v80, s24, v70
	v_fma_f32 v205, v81, s24, v71
	s_nop 0
	v_max3_f32 v70, v69, v204, v205
	v_fma_f32 v69, v175, s49, v68
	v_fma_f32 v68, v174, s48, v68
	s_nop 0
	v_fma_f32 v206, v82, s24, v68
	v_fma_f32 v207, v83, s24, v69
	s_nop 0
	v_max3_f32 v151, v70, v206, v207
.LBB0_659:
	s_nop 8
	v_mov_b32_e32 v68, v151
	s_nop 1
	v_permlane32_swap_b32_e32 v151, v68
	v_max3_f32 v171, v225, v151, v68
	v_cmp_gt_f32_e32 vcc, v171, v225
	s_cbranch_vccz .LBB0_661
	v_sub_f32_e32 v68, v225, v171
	v_exp_f32_e32 v68, v68
	s_nop 0
	v_mul_f32_e64 v64, v64, v68
	v_mul_f32_e64 v65, v65, v68
	v_mul_f32_e64 v62, v62, v68
	v_mul_f32_e64 v63, v63, v68
	v_mul_f32_e64 v60, v60, v68
	v_mul_f32_e64 v61, v61, v68
	v_mul_f32_e64 v58, v58, v68
	v_mul_f32_e64 v59, v59, v68
	v_mul_f32_e64 v56, v56, v68
	v_mul_f32_e64 v57, v57, v68
	v_mul_f32_e64 v54, v54, v68
	v_mul_f32_e64 v55, v55, v68
	v_mul_f32_e64 v52, v52, v68
	v_mul_f32_e64 v53, v53, v68
	v_mul_f32_e64 v50, v50, v68
	v_mul_f32_e64 v51, v51, v68
	v_mul_f32_e64 v48, v48, v68
	v_mul_f32_e64 v49, v49, v68
	v_mul_f32_e64 v46, v46, v68
	v_mul_f32_e64 v47, v47, v68
	v_mul_f32_e64 v44, v44, v68
	v_mul_f32_e64 v45, v45, v68
	v_mul_f32_e64 v42, v42, v68
	v_mul_f32_e64 v43, v43, v68
	v_mul_f32_e64 v40, v40, v68
	v_mul_f32_e64 v41, v41, v68
	v_mul_f32_e64 v38, v38, v68
	v_mul_f32_e64 v39, v39, v68
	v_mul_f32_e64 v36, v36, v68
	v_mul_f32_e64 v37, v37, v68
	v_mul_f32_e64 v34, v34, v68
	v_mul_f32_e64 v35, v35, v68
	v_mul_f32_e64 v32, v32, v68
	v_mul_f32_e64 v33, v33, v68
	v_mul_f32_e64 v30, v30, v68
	v_mul_f32_e64 v31, v31, v68
	v_mul_f32_e64 v28, v28, v68
	v_mul_f32_e64 v29, v29, v68
	v_mul_f32_e64 v26, v26, v68
	v_mul_f32_e64 v27, v27, v68
	v_mul_f32_e64 v24, v24, v68
	v_mul_f32_e64 v25, v25, v68
	v_mul_f32_e64 v22, v22, v68
	v_mul_f32_e64 v23, v23, v68
	v_mul_f32_e64 v20, v20, v68
	v_mul_f32_e64 v21, v21, v68
	v_mul_f32_e64 v18, v18, v68
	v_mul_f32_e64 v19, v19, v68
	v_mul_f32_e64 v16, v16, v68
	v_mul_f32_e64 v17, v17, v68
	v_mul_f32_e64 v14, v14, v68
	v_mul_f32_e64 v15, v15, v68
	v_mul_f32_e64 v12, v12, v68
	v_mul_f32_e64 v13, v13, v68
	v_mul_f32_e64 v10, v10, v68
	v_mul_f32_e64 v11, v11, v68
	v_mul_f32_e64 v8, v8, v68
	v_mul_f32_e64 v9, v9, v68
	v_mul_f32_e64 v6, v6, v68
	v_mul_f32_e64 v7, v7, v68
	v_mul_f32_e64 v4, v4, v68
	v_mul_f32_e64 v5, v5, v68
	v_mul_f32_e64 v2, v2, v68
	v_mul_f32_e64 v3, v3, v68
	v_mul_f32_e32 v66, v66, v68

; template <int DV, bool FOX>
; DI void flash(f32x16 (&O)[DV / 32], const bf16_t* __restrict__ qptr, const bf16_t* __restrict__ kg, const bf16_t* __restrict__ vtg,
;               int ntiles, int q, float slope2, const float* __restrict__ cum2, float KN, bf16_t* smem) {
;     ...
;         if (kt > 0) {
;             const int klast = kb - 1;
;             float bm = 0.f;
;             if (klast < q) bm = FOX ? cq - cklast : -slope2 * (float)(q - klast);
;             const bool pred = (q >= LT) || (sbound + bm < m - 152.f);
;             wskip = __all(pred);
;         }
.LBB0_664:
	v_subrev_u32_e32 v68, s68, v163
	v_cvt_f32_i32_e32 v68, v68
	v_cmp_le_i32_e32 vcc, s68, v154
	v_mul_f32_e64 v68, -v159, v68
	s_nop 0
	v_cndmask_b32_e32 v142, 0, v68, vcc
	v_add_f32_e64 v68, v170, v142
	v_add_f32_e64 v69, v171, v143
	s_nop 0
	v_cmp_lt_f32_e32 vcc, v68, v69
	s_or_b64 s[10:11], s[4:5], vcc
	v_cndmask_b32_e64 v68, 0, 1, s[10:11]
	v_cmp_ne_u32_e32 vcc, 0, v68
	s_cmp_eq_u64 vcc, exec
	s_cselect_b64 s[10:11], -1, 0

; DI float xsum32(float x) { auto r = __builtin_amdgcn_permlane32_swap(__float_as_uint(x), __float_as_uint(x), false, false); return __uint_as_float(r[0]) + __uint_as_float(r[1]); }
; template <int DV, bool FOX>
; DI void flash(f32x16 (&O)[DV / 32], const bf16_t* __restrict__ qptr, const bf16_t* __restrict__ kg, const bf16_t* __restrict__ vtg,
;               int ntiles, int q, float slope2, const float* __restrict__ cum2, float KN, bf16_t* smem) {
;     ...
;     l = xsum32(l);
;     const float inv = 1.0f / l;
; #pragma unroll
;     for (int dt = 0; dt < NDT; ++dt)
; #pragma unroll
;         for (int i = 0; i < 16; ++i) O[dt][i] *= inv;
; DI void ph_attn(const Params& p, bf16_t* smem, int* s_item) {
;     ...
;             float ss = 0.f;
; #pragma unroll
;             for (int dt = 0; dt < 4; ++dt)
; #pragma unroll
;                 for (int g = 0; g < 4; ++g) {
;                     const f32x4 pv = *(const f32x4*)(scr + dt * 16 + 4 * g);
; #pragma unroll
;                     for (int e = 0; e < 4; ++e) { const float o = pv[e] - lam * O0[dt][4 * g + e]; O0[dt][4 * g + e] = o; ss += o * o; }
;                 }
;             ss = xsum32(ss);
.LBB0_678:
	global_load_dwordx4 v[80:83], v[146:147], off
	global_load_dwordx4 v[76:79], v[146:147], off offset:16
	global_load_dwordx4 v[72:75], v[146:147], off offset:32
	global_load_dwordx4 v[68:71], v[146:147], off offset:48
	global_load_dwordx4 v[84:87], v[146:147], off offset:64
	global_load_dwordx4 v[88:91], v[146:147], off offset:80
	global_load_dwordx4 v[92:95], v[146:147], off offset:96
	global_load_dwordx4 v[96:99], v[146:147], off offset:112
	global_load_dwordx4 v[100:103], v[146:147], off offset:176
	global_load_dwordx4 v[104:107], v[146:147], off offset:160
	global_load_dwordx4 v[108:111], v[146:147], off offset:144
	global_load_dwordx4 v[112:115], v[146:147], off offset:128
	global_load_dwordx4 v[116:119], v[146:147], off offset:240
	global_load_dwordx4 v[120:123], v[146:147], off offset:224
	global_load_dwordx4 v[124:127], v[146:147], off offset:208
	global_load_dwordx4 v[128:131], v[146:147], off offset:192
	v_mov_b32_e32 v0, v66
	s_nop 1
	v_permlane32_swap_b32_e32 v66, v0
	v_add_f32_e32 v0, v66, v0
	v_div_scale_f32 v66, s[4:5], v0, v0, 1.0
	v_rcp_f32_e32 v67, v66
	s_waitcnt vmcnt(18)
	v_div_scale_f32 v132, vcc, 1.0, v0, 1.0
	v_fma_f32 v133, -v66, v67, 1.0
	v_fmac_f32_e32 v67, v133, v67
	v_mul_f32_e32 v133, v132, v67
	v_fma_f32 v134, -v66, v133, v132
	v_fmac_f32_e32 v133, v134, v67
	v_fma_f32 v66, -v66, v133, v132
	v_div_fmas_f32 v66, v66, v67, v133
	v_div_fixup_f32 v0, v66, v0, 1.0
	v_mul_f32_e64 v50, v50, v0
	v_mul_f32_e64 v51, v51, v0
	v_mul_f32_e64 v36, v36, v0
	v_mul_f32_e64 v37, v37, v0
	v_mul_f32_e64 v46, v46, v0
	v_mul_f32_e64 v47, v47, v0
	v_mul_f32_e64 v52, v52, v0
	v_mul_f32_e64 v53, v53, v0
	v_mul_f32_e64 v158, v48, v0
	v_mul_f32_e64 v159, v49, v0
	v_mul_f32_e64 v54, v54, v0
	v_mul_f32_e64 v55, v55, v0
	v_mul_f32_e64 v56, v56, v0
	v_mul_f32_e64 v57, v57, v0
	v_mul_f32_e64 v58, v58, v0
	v_mul_f32_e64 v59, v59, v0
	v_mul_f32_e64 v60, v60, v0
	v_mul_f32_e64 v61, v61, v0
	v_mul_f32_e64 v132, v62, v0
	v_mul_f32_e64 v133, v63, v0
	v_mul_f32_e64 v134, v64, v0
	v_mul_f32_e64 v135, v65, v0
	v_mul_f32_e64 v34, v34, v0
	v_mul_f32_e64 v35, v35, v0
	v_mul_f32_e64 v38, v38, v0
	v_mul_f32_e64 v39, v39, v0
	s_waitcnt vmcnt(16)
	v_mul_f32_e64 v138, v44, v0
	v_mul_f32_e64 v139, v45, v0
	v_mul_f32_e64 v40, v40, v0
	v_mul_f32_e64 v41, v41, v0
	v_mul_f32_e64 v136, v42, v0
	v_mul_f32_e64 v137, v43, v0
	v_mul_f32_e64 v18, v18, v0
	v_mul_f32_e64 v19, v19, v0
	v_mul_f32_e64 v20, v20, v0
	v_mul_f32_e64 v21, v21, v0
	v_mul_f32_e64 v2, v2, v0
	v_mul_f32_e64 v3, v3, v0
	v_mul_f32_e64 v4, v4, v0
	v_mul_f32_e64 v5, v5, v0
	v_mul_f32_e64 v8, v8, v0
	v_mul_f32_e64 v9, v9, v0
	v_mul_f32_e64 v12, v12, v0
	v_mul_f32_e64 v13, v13, v0
	v_cmp_gt_i32_e32 vcc, s25, v154
	s_waitcnt vmcnt(15)
	v_fma_f32 v80, -v140, v50, v80
	v_fma_f32 v81, -v141, v51, v81
	v_fma_f32 v82, -v140, v52, v82
	v_fma_f32 v83, -v141, v53, v83
	s_waitcnt vmcnt(14)
	v_fma_f32 v76, -v140, v54, v76
	v_fma_f32 v77, -v141, v55, v77
	v_mul_f32_e32 v50, v83, v83
	s_waitcnt vmcnt(11)
	v_fma_f32 v48, -v140, v36, v86
	v_fma_f32 v49, -v141, v37, v87
	v_mul_f32_e32 v54, v77, v77
	v_fma_f32 v66, -v140, v56, v78
	v_fma_f32 v67, -v141, v57, v79
	s_waitcnt vmcnt(8)
	v_fma_f32 v36, -v140, v46, v96
	v_fma_f32 v37, -v141, v47, v97
	v_mul_f32_e32 v46, v81, v81
	v_fma_f32 v47, v81, v81, v46
	v_fma_f32 v46, v80, v80, v46
	v_mul_f32_e32 v56, v67, v67
	v_fma_f32 v46, v82, v82, v46
	v_fma_f32 v47, v83, v83, v47
	v_fma_f32 v64, -v140, v58, v72
	v_fma_f32 v65, -v141, v59, v73
	v_add_f32_e64 v46, v50, v46
	v_add_f32_e64 v47, v50, v47
	v_fma_f32 v46, v76, v76, v46
	v_fma_f32 v47, v77, v77, v47
	v_fma_f32 v62, -v140, v60, v74
	v_fma_f32 v63, -v141, v61, v75
	v_add_f32_e64 v46, v54, v46
	v_add_f32_e64 v47, v54, v47
	v_fma_f32 v46, v66, v66, v46
	v_fma_f32 v47, v67, v67, v47
	v_fma_f32 v60, -v140, v132, v68
	v_fma_f32 v61, -v141, v133, v69
	v_add_f32_e64 v46, v56, v46
	v_add_f32_e64 v47, v56, v47
	v_mul_f32_e32 v68, v65, v65
	v_fma_f32 v46, v64, v64, v46
	v_fma_f32 v47, v65, v65, v47
	v_fma_f32 v58, -v140, v134, v70
	v_fma_f32 v59, -v141, v135, v71
	v_add_f32_e64 v46, v68, v46
	v_add_f32_e64 v47, v68, v47
	v_mul_f32_e32 v70, v63, v63
	v_fma_f32 v46, v62, v62, v46
	v_fma_f32 v47, v63, v63, v47
	v_mul_f32_e32 v72, v61, v61
	v_add_f32_e64 v46, v70, v46
	v_add_f32_e64 v47, v70, v47
	v_fma_f32 v46, v60, v60, v46
	v_fma_f32 v47, v61, v61, v47
	v_mul_f32_e32 v74, v59, v59
	v_add_f32_e64 v46, v72, v46
	v_add_f32_e64 v47, v72, v47
	v_fma_f32 v46, v58, v58, v46
	v_fma_f32 v47, v59, v59, v47
	v_fma_f32 v52, -v140, v34, v84
	v_fma_f32 v53, -v141, v35, v85
	v_add_f32_e64 v46, v74, v46
	v_add_f32_e64 v47, v74, v47
	v_mul_f32_e32 v78, v53, v53
	v_fma_f32 v46, v52, v52, v46
	v_fma_f32 v47, v53, v53, v47
	v_mul_f32_e32 v84, v49, v49
	v_add_f32_e64 v46, v78, v46
	v_add_f32_e64 v47, v78, v47
	v_fma_f32 v46, v48, v48, v46
	v_fma_f32 v47, v49, v49, v47
	v_fma_f32 v44, -v140, v38, v88
	v_fma_f32 v45, -v141, v39, v89
	v_add_f32_e64 v46, v84, v46
	v_add_f32_e64 v47, v84, v47
	v_mul_f32_e32 v86, v45, v45
	v_fma_f32 v46, v44, v44, v46
	v_fma_f32 v47, v45, v45, v47
	v_fma_f32 v42, -v140, v40, v90
	v_fma_f32 v43, -v141, v41, v91
	v_add_f32_e64 v46, v86, v46
	v_add_f32_e64 v47, v86, v47
	v_mul_f32_e32 v88, v43, v43
	v_fma_f32 v46, v42, v42, v46
	v_fma_f32 v47, v43, v43, v47
	v_fma_f32 v40, -v140, v136, v92
	v_fma_f32 v41, -v141, v137, v93
	v_add_f32_e64 v46, v88, v46
	v_add_f32_e64 v47, v88, v47
	v_mul_f32_e32 v90, v41, v41
	v_fma_f32 v46, v40, v40, v46
	v_fma_f32 v47, v41, v41, v47
	v_fma_f32 v38, -v140, v138, v94
	v_fma_f32 v39, -v141, v139, v95
	v_add_f32_e64 v46, v90, v46
	v_add_f32_e64 v47, v90, v47
	v_mul_f32_e32 v92, v39, v39
	v_fma_f32 v46, v38, v38, v46
	v_fma_f32 v47, v39, v39, v47
	v_mul_f32_e32 v94, v37, v37
	v_add_f32_e64 v46, v92, v46
	v_add_f32_e64 v47, v92, v47
	v_fma_f32 v46, v36, v36, v46
	v_fma_f32 v47, v37, v37, v47
	v_fma_f32 v34, -v140, v158, v98
	v_fma_f32 v35, -v141, v159, v99
	v_add_f32_e64 v46, v94, v46
	v_add_f32_e64 v47, v94, v47
	v_mul_f32_e32 v96, v35, v35
	v_fma_f32 v46, v34, v34, v46
	v_fma_f32 v47, v35, v35, v47
	s_waitcnt vmcnt(4)
; DI float xsum32(float x) { auto r = __builtin_amdgcn_permlane32_swap(__float_as_uint(x), __float_as_uint(x), false, false); return __uint_as_float(r[0]) + __uint_as_float(r[1]); }
; DI void ph_attn(const Params& p, bf16_t* smem, int* s_item) {
;     ...
;             float ss = 0.f;
; #pragma unroll
;             for (int dt = 0; dt < 4; ++dt)
; #pragma unroll
;                 for (int g = 0; g < 4; ++g) {
;                     const f32x4 pv = *(const f32x4*)(scr + dt * 16 + 4 * g);
; #pragma unroll
;                     for (int e = 0; e < 4; ++e) { const float o = pv[e] - lam * O0[dt][4 * g + e]; O0[dt][4 * g + e] = o; ss += o * o; }
;                 }
;             ss = xsum32(ss);
	v_fma_f32 v54, -v140, v18, v112
	v_fma_f32 v55, -v141, v19, v113
	v_add_f32_e64 v46, v96, v46
	v_add_f32_e64 v47, v96, v47
	v_fma_f32 v18, v54, v54, v46
	v_fma_f32 v19, v55, v55, v47
	v_mul_f32_e32 v46, v55, v55
	v_add_f32_e64 v18, v46, v18
	v_add_f32_e64 v19, v46, v19
	v_fma_f32 v56, -v140, v20, v114
	v_fma_f32 v57, -v141, v21, v115
	s_waitcnt vmcnt(0)
	v_fma_f32 v2, -v140, v2, v128
	v_fma_f32 v3, -v141, v3, v129
	v_fma_f32 v18, v56, v56, v18
	v_fma_f32 v19, v57, v57, v19
	v_mul_f32_e32 v20, v57, v57
	v_add_f32_e64 v18, v20, v18
	v_add_f32_e64 v19, v20, v19
	v_mul_f32_e64 v20, v22, v0
	v_mul_f32_e64 v21, v23, v0
	v_fma_f32 v8, -v140, v8, v126
	v_fma_f32 v9, -v141, v9, v127
	v_fma_f32 v46, -v140, v20, v108
	v_fma_f32 v47, -v141, v21, v109
	v_fma_f32 v12, -v140, v12, v122
	v_fma_f32 v13, -v141, v13, v123
	v_fma_f32 v18, v46, v46, v18
	v_fma_f32 v19, v47, v47, v19
	v_mul_f32_e32 v20, v47, v47
	v_add_f32_e64 v18, v20, v18
	v_add_f32_e64 v19, v20, v19
	v_mul_f32_e64 v20, v24, v0
	v_mul_f32_e64 v21, v25, v0
	s_nop 0
	v_fma_f32 v50, -v140, v20, v110
	v_fma_f32 v51, -v141, v21, v111
	s_nop 0
	v_fma_f32 v18, v50, v50, v18
	v_fma_f32 v19, v51, v51, v19
	v_mul_f32_e32 v20, v51, v51
	v_add_f32_e64 v18, v20, v18
	v_add_f32_e64 v19, v20, v19
	v_mul_f32_e64 v20, v26, v0
	v_mul_f32_e64 v21, v27, v0
	s_nop 0
	v_fma_f32 v24, -v140, v20, v104
	v_fma_f32 v25, -v141, v21, v105
	s_nop 0
	v_fma_f32 v18, v24, v24, v18
	v_fma_f32 v19, v25, v25, v19
	v_mul_f32_e32 v20, v25, v25
	v_add_f32_e64 v18, v20, v18
	v_add_f32_e64 v19, v20, v19
	v_mul_f32_e64 v20, v28, v0
	v_mul_f32_e64 v21, v29, v0
	s_nop 0
	v_fma_f32 v26, -v140, v20, v106
	v_fma_f32 v27, -v141, v21, v107
	s_nop 0
	v_fma_f32 v18, v26, v26, v18
	v_fma_f32 v19, v27, v27, v19
	v_mul_f32_e32 v20, v27, v27
	v_add_f32_e64 v21, v20, v19
	v_add_f32_e64 v20, v20, v18
	v_mul_f32_e64 v18, v30, v0
	v_mul_f32_e64 v19, v31, v0
	s_nop 0
	v_fma_f32 v18, -v140, v18, v100
	v_fma_f32 v19, -v141, v19, v101
	s_nop 0
	v_fma_f32 v20, v18, v18, v20
	v_fma_f32 v21, v19, v19, v21
	v_mul_f32_e32 v22, v19, v19
	v_add_f32_e64 v23, v22, v21
	v_add_f32_e64 v22, v22, v20
	v_mul_f32_e64 v20, v32, v0
	v_mul_f32_e64 v21, v33, v0
	s_nop 0
	v_fma_f32 v20, -v140, v20, v102
	v_fma_f32 v21, -v141, v21, v103
	s_nop 0
	v_fma_f32 v22, v20, v20, v22
	v_fma_f32 v23, v21, v21, v23
	v_mul_f32_e32 v28, v21, v21
	v_add_f32_e64 v22, v28, v22
	v_add_f32_e64 v23, v28, v23
	v_fma_f32 v22, v2, v2, v22
	v_fma_f32 v23, v3, v3, v23
	v_mul_f32_e32 v28, v3, v3
	v_add_f32_e64 v29, v28, v23
	v_add_f32_e64 v28, v28, v22
	v_fma_f32 v22, -v140, v4, v130
	v_fma_f32 v23, -v141, v5, v131
	s_nop 0
	v_fma_f32 v4, v22, v22, v28
	v_fma_f32 v5, v23, v23, v29
	v_mul_f32_e32 v28, v23, v23
	v_add_f32_e64 v29, v28, v5
	v_add_f32_e64 v28, v28, v4
	v_mul_f32_e64 v4, v6, v0
	v_mul_f32_e64 v5, v7, v0
	s_nop 0
	v_fma_f32 v4, -v140, v4, v124
	v_fma_f32 v5, -v141, v5, v125
	s_nop 0
	v_fma_f32 v6, v4, v4, v28
	v_fma_f32 v7, v5, v5, v29
	v_mul_f32_e32 v28, v5, v5
	v_add_f32_e64 v6, v28, v6
	v_add_f32_e64 v7, v28, v7
	v_fma_f32 v6, v8, v8, v6
	v_fma_f32 v7, v9, v9, v7
	v_mul_f32_e32 v28, v9, v9
	v_add_f32_e64 v29, v28, v7
	v_add_f32_e64 v28, v28, v6
	v_mul_f32_e64 v6, v10, v0
	v_mul_f32_e64 v7, v11, v0
	s_nop 0
	v_fma_f32 v6, -v140, v6, v120
	v_fma_f32 v7, -v141, v7, v121
	s_nop 0
	v_fma_f32 v10, v6, v6, v28
	v_fma_f32 v11, v7, v7, v29
	v_mul_f32_e32 v28, v7, v7
	v_add_f32_e64 v10, v28, v10
	v_add_f32_e64 v11, v28, v11
	v_fma_f32 v10, v12, v12, v10
	v_fma_f32 v11, v13, v13, v11
	v_mul_f32_e32 v28, v13, v13
	v_add_f32_e64 v29, v28, v11
	v_add_f32_e64 v28, v28, v10
	v_mul_f32_e64 v10, v14, v0
	v_mul_f32_e64 v11, v15, v0
	s_nop 0
	v_fma_f32 v10, -v140, v10, v116
	v_fma_f32 v11, -v141, v11, v117
	s_nop 0
	v_fma_f32 v14, v10, v10, v28
	v_fma_f32 v15, v11, v11, v29
	v_mul_f32_e32 v28, v11, v11
	v_add_f32_e64 v29, v28, v15
	v_add_f32_e64 v28, v28, v14
	v_mul_f32_e64 v14, v16, v0
	v_mul_f32_e64 v15, v17, v0
	s_nop 0
	v_fma_f32 v14, -v140, v14, v118
	v_fma_f32 v15, -v141, v15, v119
	s_nop 0
	v_fma_f32 v16, v14, v14, v28
	v_fma_f32 v17, v15, v15, v29
	v_mul_f32_e32 v0, v15, v15
	v_add_f32_e64 v16, v0, v16
	v_add_f32_e64 v17, v0, v17
	v_mov_b32_e32 v0, v16
	s_nop 1
	v_permlane32_swap_b32_e32 v16, v0
	s_and_saveexec_b64 s[4:5], vcc
	s_xor_b64 s[4:5], exec, s[4:5]
	s_cbranch_execz .LBB0_680
; DI unsigned cvt_pk(float lo, float hi) { f32x2 v = {lo, hi}; bf16x2v b = __builtin_convertvector(v, bf16x2v); return __builtin_bit_cast(unsigned, b); }
; DI float xsum32(float x) { auto r = __builtin_amdgcn_permlane32_swap(__float_as_uint(x), __float_as_uint(x), false, false); return __uint_as_float(r[0]) + __uint_as_float(r[1]); }
; DI void ph_attn(const Params& p, bf16_t* smem, int* s_item) {
;     ...
;             ss = xsum32(ss);
;             const float rn = __frsqrt_rn(ss * (1.0f / 128.0f) + 1e-6f) * 0.8f;
;             if (q < LT) {
;                 bf16_t* d = MIX + qrow * 1024 + hd * 128;
; #pragma unroll
;                 for (int dt = 0; dt < 4; ++dt)
; #pragma unroll
;                     for (int g = 0; g < 4; ++g) {
;                         const int dv = dt * 32 + 8 * g + 4 * h;
;                         const f32x4 gg = *(const f32x4*)(p.subln + dv);
;                         u32x2 wv; wv[0] = cvt_pk(O0[dt][4 * g] * rn * gg[0], O0[dt][4 * g + 1] * rn * gg[1]);
;                         wv[1] = cvt_pk(O0[dt][4 * g + 2] * rn * gg[2], O0[dt][4 * g + 3] * rn * gg[3]);
;                         *(u32x2*)(d + dv) = wv;
;                     }
	global_load_dwordx4 v[28:31], v[148:149], off
	v_add_f32_e32 v32, v16, v0
	v_fmamk_f32 v32, v32, 0x3c000000, v213
	v_rsq_f32_e32 v68, v32
	v_lshlrev_b64 v[16:17], 11, v[152:153]
	s_lshl_b32 s20, s70, 1
	v_lshl_add_u64 v[16:17], s[40:41], 0, v[16:17]
	v_lshlrev_b32_e32 v0, 1, v144
	v_lshl_add_u64 v[16:17], v[16:17], 0, s[20:21]
	v_lshl_add_u64 v[32:33], v[16:17], 0, v[0:1]
	v_mul_f32_e32 v0, 0x3f4ccccd, v68
	v_mul_f32_e64 v16, v80, v0
	v_mul_f32_e64 v17, v81, v0
	v_mul_f32_e64 v68, v82, v0
	v_mul_f32_e64 v69, v83, v0
	v_mul_f32_e64 v66, v66, v0
	v_mul_f32_e64 v67, v67, v0
	v_mul_f32_e64 v62, v62, v0
	v_mul_f32_e64 v63, v63, v0
	v_mul_f32_e64 v58, v58, v0
	v_mul_f32_e64 v59, v59, v0
	v_mul_f32_e64 v48, v48, v0
	v_mul_f32_e64 v49, v49, v0
	v_mul_f32_e64 v42, v42, v0
	v_mul_f32_e64 v43, v43, v0
	v_mul_f32_e64 v38, v38, v0
	v_mul_f32_e64 v39, v39, v0
	v_mul_f32_e64 v34, v34, v0
	v_mul_f32_e64 v35, v35, v0
	v_mul_f32_e64 v2, v2, v0
	v_mul_f32_e64 v3, v3, v0
	v_mul_f32_e64 v6, v6, v0
	v_mul_f32_e64 v7, v7, v0
	s_waitcnt vmcnt(0)
	v_mul_f32_e64 v16, v16, v28
	v_mul_f32_e64 v17, v17, v29
	v_mul_f32_e64 v28, v68, v30
	v_mul_f32_e64 v29, v69, v31
	v_cvt_pk_bf16_f32 v16, v16, v17
	v_cvt_pk_bf16_f32 v17, v28, v29
	global_store_dwordx2 v[32:33], v[16:17], off
	global_load_dwordx4 v[28:31], v[148:149], off offset:32
	v_mul_f32_e64 v16, v76, v0
	v_mul_f32_e64 v17, v77, v0
	s_waitcnt vmcnt(0)
	v_mul_f32_e64 v16, v16, v28
	v_mul_f32_e64 v17, v17, v29
	v_mul_f32_e64 v28, v66, v30
	v_mul_f32_e64 v29, v67, v31
	v_cvt_pk_bf16_f32 v16, v16, v17
	v_cvt_pk_bf16_f32 v17, v28, v29
	global_store_dwordx2 v[32:33], v[16:17], off offset:16
	global_load_dwordx4 v[28:31], v[148:149], off offset:64
	v_mul_f32_e64 v16, v64, v0
	v_mul_f32_e64 v17, v65, v0
	s_waitcnt vmcnt(0)
	v_mul_f32_e64 v16, v16, v28
	v_mul_f32_e64 v17, v17, v29
	v_mul_f32_e64 v28, v62, v30
	v_mul_f32_e64 v29, v63, v31
	v_cvt_pk_bf16_f32 v16, v16, v17
	v_cvt_pk_bf16_f32 v17, v28, v29
	global_store_dwordx2 v[32:33], v[16:17], off offset:32
	global_load_dwordx4 v[28:31], v[148:149], off offset:96
	v_mul_f32_e64 v16, v60, v0
	v_mul_f32_e64 v17, v61, v0
	s_waitcnt vmcnt(0)
	v_mul_f32_e64 v16, v16, v28
	v_mul_f32_e64 v17, v17, v29
	v_mul_f32_e64 v28, v58, v30
	v_mul_f32_e64 v29, v59, v31
	v_cvt_pk_bf16_f32 v16, v16, v17
	v_cvt_pk_bf16_f32 v17, v28, v29
	global_store_dwordx2 v[32:33], v[16:17], off offset:48
	global_load_dwordx4 v[28:31], v[148:149], off offset:128
	v_mul_f32_e64 v16, v52, v0
	v_mul_f32_e64 v17, v53, v0
	s_waitcnt vmcnt(0)
	v_mul_f32_e64 v16, v16, v28
	v_mul_f32_e64 v17, v17, v29
	v_mul_f32_e64 v28, v48, v30
	v_mul_f32_e64 v29, v49, v31
	v_cvt_pk_bf16_f32 v16, v16, v17
	v_cvt_pk_bf16_f32 v17, v28, v29
	global_store_dwordx2 v[32:33], v[16:17], off offset:64
	global_load_dwordx4 v[28:31], v[148:149], off offset:160
	v_mul_f32_e64 v16, v44, v0
	v_mul_f32_e64 v17, v45, v0
	s_waitcnt vmcnt(0)
	v_mul_f32_e64 v16, v16, v28
	v_mul_f32_e64 v17, v17, v29
	v_mul_f32_e64 v28, v42, v30
	v_mul_f32_e64 v29, v43, v31
	v_cvt_pk_bf16_f32 v16, v16, v17
	v_cvt_pk_bf16_f32 v17, v28, v29
	global_store_dwordx2 v[32:33], v[16:17], off offset:80
	global_load_dwordx4 v[28:31], v[148:149], off offset:192
	v_mul_f32_e64 v16, v40, v0
	v_mul_f32_e64 v17, v41, v0
	s_waitcnt vmcnt(0)
	v_mul_f32_e64 v16, v16, v28
	v_mul_f32_e64 v17, v17, v29
	v_mul_f32_e64 v28, v38, v30
	v_mul_f32_e64 v29, v39, v31
	v_cvt_pk_bf16_f32 v16, v16, v17
	v_cvt_pk_bf16_f32 v17, v28, v29
	global_store_dwordx2 v[32:33], v[16:17], off offset:96
	global_load_dwordx4 v[28:31], v[148:149], off offset:224
	v_mul_f32_e64 v16, v36, v0
	v_mul_f32_e64 v17, v37, v0
	s_waitcnt vmcnt(0)
; DI unsigned cvt_pk(float lo, float hi) { f32x2 v = {lo, hi}; bf16x2v b = __builtin_convertvector(v, bf16x2v); return __builtin_bit_cast(unsigned, b); }
; DI void ph_attn(const Params& p, bf16_t* smem, int* s_item) {
;     ...
;                 bf16_t* d = MIX + qrow * 1024 + hd * 128;
; #pragma unroll
;                 for (int dt = 0; dt < 4; ++dt)
; #pragma unroll
;                     for (int g = 0; g < 4; ++g) {
;                         const int dv = dt * 32 + 8 * g + 4 * h;
;                         const f32x4 gg = *(const f32x4*)(p.subln + dv);
;                         u32x2 wv; wv[0] = cvt_pk(O0[dt][4 * g] * rn * gg[0], O0[dt][4 * g + 1] * rn * gg[1]);
;                         wv[1] = cvt_pk(O0[dt][4 * g + 2] * rn * gg[2], O0[dt][4 * g + 3] * rn * gg[3]);
;                         *(u32x2*)(d + dv) = wv;
;                     }
	v_mul_f32_e64 v16, v16, v28
	v_mul_f32_e64 v17, v17, v29
	v_mul_f32_e64 v28, v34, v30
	v_mul_f32_e64 v29, v35, v31
	v_cvt_pk_bf16_f32 v16, v16, v17
	v_cvt_pk_bf16_f32 v17, v28, v29
	global_store_dwordx2 v[32:33], v[16:17], off offset:112
	global_load_dwordx4 v[28:31], v[148:149], off offset:256
	v_mul_f32_e64 v16, v54, v0
	v_mul_f32_e64 v17, v55, v0
	v_mul_f32_e64 v34, v56, v0
	v_mul_f32_e64 v35, v57, v0
	s_waitcnt vmcnt(0)
	v_mul_f32_e64 v16, v16, v28
	v_mul_f32_e64 v17, v17, v29
	v_mul_f32_e64 v28, v34, v30
	v_mul_f32_e64 v29, v35, v31
	v_cvt_pk_bf16_f32 v16, v16, v17
	v_cvt_pk_bf16_f32 v17, v28, v29
	global_store_dwordx2 v[32:33], v[16:17], off offset:128
	global_load_dwordx4 v[28:31], v[148:149], off offset:288
	v_mul_f32_e64 v16, v46, v0
	v_mul_f32_e64 v17, v47, v0
	v_mul_f32_e64 v34, v50, v0
	v_mul_f32_e64 v35, v51, v0
	s_waitcnt vmcnt(0)
	v_mul_f32_e64 v16, v16, v28
	v_mul_f32_e64 v17, v17, v29
	v_mul_f32_e64 v28, v34, v30
	v_mul_f32_e64 v29, v35, v31
	v_cvt_pk_bf16_f32 v16, v16, v17
	v_cvt_pk_bf16_f32 v17, v28, v29
	global_store_dwordx2 v[32:33], v[16:17], off offset:144
	global_load_dwordx4 v[28:31], v[148:149], off offset:320
	v_mul_f32_e64 v16, v24, v0
	v_mul_f32_e64 v17, v25, v0
	v_mul_f32_e64 v24, v26, v0
	v_mul_f32_e64 v25, v27, v0
	s_waitcnt vmcnt(0)
	v_mul_f32_e64 v16, v16, v28
	v_mul_f32_e64 v17, v17, v29
	v_mul_f32_e64 v24, v24, v30
	v_mul_f32_e64 v25, v25, v31
	v_cvt_pk_bf16_f32 v16, v16, v17
	v_cvt_pk_bf16_f32 v17, v24, v25
	global_store_dwordx2 v[32:33], v[16:17], off offset:160
	global_load_dwordx4 v[24:27], v[148:149], off offset:352
	v_mul_f32_e64 v16, v18, v0
	v_mul_f32_e64 v17, v19, v0
	v_mul_f32_e64 v18, v20, v0
	v_mul_f32_e64 v19, v21, v0
	v_mul_f32_e64 v20, v22, v0
	v_mul_f32_e64 v21, v23, v0
	s_waitcnt vmcnt(0)
	v_mul_f32_e64 v16, v16, v24
	v_mul_f32_e64 v17, v17, v25
	v_mul_f32_e64 v18, v18, v26
	v_mul_f32_e64 v19, v19, v27
	v_cvt_pk_bf16_f32 v16, v16, v17
	v_cvt_pk_bf16_f32 v17, v18, v19
	global_store_dwordx2 v[32:33], v[16:17], off offset:176
	global_load_dwordx4 v[16:19], v[148:149], off offset:384
	s_waitcnt vmcnt(0)
	v_mul_f32_e64 v2, v2, v16
	v_mul_f32_e64 v3, v3, v17
	v_mul_f32_e64 v16, v20, v18
	v_mul_f32_e64 v17, v21, v19
	v_cvt_pk_bf16_f32 v2, v2, v3
	v_cvt_pk_bf16_f32 v3, v16, v17
	global_store_dwordx2 v[32:33], v[2:3], off offset:192
	global_load_dwordx4 v[16:19], v[148:149], off offset:416
	v_mul_f32_e64 v2, v4, v0
	v_mul_f32_e64 v3, v5, v0
	v_mul_f32_e64 v4, v8, v0
	v_mul_f32_e64 v5, v9, v0
	v_mul_f32_e64 v8, v12, v0
	v_mul_f32_e64 v9, v13, v0
	s_waitcnt vmcnt(0)
	v_mul_f32_e64 v2, v2, v16
	v_mul_f32_e64 v3, v3, v17
	v_mul_f32_e64 v4, v4, v18
	v_mul_f32_e64 v5, v5, v19
	v_cvt_pk_bf16_f32 v2, v2, v3
	v_cvt_pk_bf16_f32 v3, v4, v5
	global_store_dwordx2 v[32:33], v[2:3], off offset:208
	global_load_dwordx4 v[2:5], v[148:149], off offset:448
	s_waitcnt vmcnt(0)
	v_mul_f32_e64 v2, v6, v2
	v_mul_f32_e64 v3, v7, v3
	v_mul_f32_e64 v4, v8, v4
	v_mul_f32_e64 v5, v9, v5
	v_cvt_pk_bf16_f32 v2, v2, v3
	v_cvt_pk_bf16_f32 v3, v4, v5
	global_store_dwordx2 v[32:33], v[2:3], off offset:224
	global_load_dwordx4 v[2:5], v[148:149], off offset:480
	v_mul_f32_e64 v6, v10, v0
	v_mul_f32_e64 v7, v11, v0
	v_mul_f32_e64 v8, v14, v0
	v_mul_f32_e64 v9, v15, v0
	s_waitcnt vmcnt(0)
	v_mul_f32_e64 v2, v6, v2
	v_mul_f32_e64 v3, v7, v3
	v_mul_f32_e64 v4, v8, v4
	v_mul_f32_e64 v5, v9, v5
	v_cvt_pk_bf16_f32 v2, v2, v3
	v_cvt_pk_bf16_f32 v3, v4, v5
	global_store_dwordx2 v[32:33], v[2:3], off offset:240

; template <int DV, bool FOX>
; DI void flash(f32x16 (&O)[DV / 32], const bf16_t* __restrict__ qptr, const bf16_t* __restrict__ kg, const bf16_t* __restrict__ vtg,
;               int ntiles, int q, float slope2, const float* __restrict__ cum2, float KN, bf16_t* smem) {
;     ...
;         f32x16 s[2];
; #pragma unroll
;         for (int sub = 0; sub < 2; ++sub) {
;             s[sub] = zero16();
; #pragma unroll
;             for (int ks = 0; ks < 4; ++ks) {
;                 const bf16x8 a = *(const bf16x8*)(Ks + (sub * 32 + pr) * 72 + ks * 16 + h * 8);
;                 s[sub] = mfma32(a, qf[ks], s[sub]);
;             }
;         }
;         float mx = -INFINITY;
;         if (kb + 63 < qlo) {
; #pragma unroll
;             for (int sub = 0; sub < 2; ++sub) {
; #pragma unroll
;                 for (int i8 = 0; i8 < 2; ++i8) {
;                     const int k0 = kb + sub * 32 + 16 * i8 + 8 * h;
;                     float ck[8];
;                     float base = 0.f;
;                     if (FOX) {
;                         const f32x4 c0 = *(const f32x4*)(cum2 + k0), c1v = *(const f32x4*)(cum2 + k0 + 4);
;                         ck[0] = c0[0]; ck[1] = c0[1]; ck[2] = c0[2]; ck[3] = c0[3]; ck[4] = c1v[0]; ck[5] = c1v[1]; ck[6] = c1v[2]; ck[7] = c1v[3];
;                     } else base = -slope2 * (float)(q - k0);
; #pragma unroll
;                     for (int e = 0; e < 8; ++e) {
;                         const float bias = FOX ? cq - ck[e] : fmaf(slope2, (float)e, base);
;                         const float t = fmaf(s[sub][8 * i8 + e], c1, bias);
;                         s[sub][8 * i8 + e] = t;
;                         mx = fmaxf(mx, t);
;                     }
;                 }
;             }
;         } else {
; #pragma unroll
;             for (int sub = 0; sub < 2; ++sub) {
; #pragma unroll
;                 for (int i8 = 0; i8 < 2; ++i8) {
;                     const int k0 = kb + sub * 32 + 16 * i8 + 8 * h;
;                     float ck[8];
;                     if (FOX) {
;                         const f32x4 c0 = *(const f32x4*)(cum2 + k0), c1v = *(const f32x4*)(cum2 + k0 + 4);
;                         ck[0] = c0[0]; ck[1] = c0[1]; ck[2] = c0[2]; ck[3] = c0[3]; ck[4] = c1v[0]; ck[5] = c1v[1]; ck[6] = c1v[2]; ck[7] = c1v[3];
;                     }
; #pragma unroll
;                     for (int e = 0; e < 8; ++e) {
.LBB0_699:
	s_sub_i32 s52, s67, s69
	s_cmp_gt_i32 s52, -1
	s_cselect_b64 s[50:51], -1, 0
	s_cmp_lt_i32 s52, 0
	s_cbranch_scc1 .LBB0_708
	s_lshl_b32 s70, s52, 6
	s_cmp_gt_i32 s70, s61
	s_cselect_b64 s[52:53], -1, 0
	s_or_b64 s[52:53], s[52:53], s[10:11]
	s_and_b64 vcc, exec, s[52:53]
	s_cbranch_vccnz .LBB0_709
	s_or_b32 s52, s69, s68
	s_mulk_i32 s52, 0x4800
	v_add_u32_e32 v171, s52, v169
	v_add_u32_e32 v0, v171, v155
	ds_read_b128 v[36:39], v0
	ds_read_b128 v[40:43], v0 offset:32
	s_or_b32 s52, s70, 63
	s_cmp_lt_i32 s52, s43
	s_mov_b64 s[52:53], -1
	s_waitcnt lgkmcnt(1)
	v_mfma_f32_32x32x16_bf16 v[52:67], v[36:39], v[68:71], 0
	s_waitcnt lgkmcnt(0)
	v_mfma_f32_32x32x16_bf16 v[52:67], v[40:43], v[72:75], v[52:67]
	ds_read_b128 v[36:39], v0 offset:64
	ds_read_b128 v[40:43], v0 offset:96
	s_waitcnt lgkmcnt(1)
	v_mfma_f32_32x32x16_bf16 v[52:67], v[36:39], v[76:79], v[52:67]
	ds_read_b128 v[36:39], v0 offset:4608
	ds_read_b128 v[100:103], v0 offset:4640
	s_waitcnt lgkmcnt(2)
	v_mfma_f32_32x32x16_bf16 v[52:67], v[40:43], v[80:83], v[52:67]
	s_waitcnt lgkmcnt(1)
	v_mfma_f32_32x32x16_bf16 v[36:51], v[36:39], v[68:71], 0
	s_waitcnt lgkmcnt(0)
	v_mfma_f32_32x32x16_bf16 v[36:51], v[100:103], v[72:75], v[36:51]
	ds_read_b128 v[100:103], v0 offset:4672
	ds_read_b128 v[120:123], v0 offset:4704
	v_or_b32_e32 v0, s70, v145
	v_lshl_add_u64 v[118:119], v[0:1], 2, s[14:15]
	s_waitcnt lgkmcnt(1)
	v_mfma_f32_32x32x16_bf16 v[36:51], v[100:103], v[76:79], v[36:51]
	global_load_dwordx4 v[100:103], v[118:119], off offset:16
	global_load_dwordx4 v[104:107], v[118:119], off
	s_waitcnt vmcnt(1)
	v_add_f32_e64 v100, v108, -v100
	v_add_f32_e64 v101, v109, -v101
	s_waitcnt lgkmcnt(0)
	v_mfma_f32_32x32x16_bf16 v[36:51], v[120:123], v[80:83], v[36:51]
	s_cbranch_scc1 .LBB0_703
	v_or_b32_e32 v136, 16, v0
	v_mov_b32_e32 v137, v1
	v_lshl_add_u64 v[120:121], v[136:137], 2, s[14:15]
	global_load_dwordx4 v[128:131], v[120:121], off offset:16
	global_load_dwordx4 v[132:135], v[120:121], off
	v_or_b32_e32 v166, 32, v0
	v_mov_b32_e32 v167, v1
	v_lshl_add_u64 v[120:121], v[166:167], 2, s[14:15]
	global_load_dwordx4 v[156:159], v[120:121], off
	global_load_dwordx4 v[162:165], v[120:121], off offset:16
	v_or_b32_e32 v138, 5, v0
	v_or_b32_e32 v139, 4, v0
	v_fma_f32 v124, v56, s24, v100
	v_fma_f32 v125, v57, s24, v101
	v_cmp_le_i32_e32 vcc, v138, v35
	v_or_b32_e32 v182, 48, v0
	v_mov_b32_e32 v183, v1
	v_cndmask_b32_e32 v121, v216, v125, vcc
	v_cmp_le_i32_e32 vcc, v139, v154
	s_waitcnt vmcnt(4)
	v_sub_f32_e32 v117, v108, v104
	v_sub_f32_e32 v137, v108, v105
	v_cndmask_b32_e32 v120, v216, v124, vcc
	v_lshl_add_u64 v[124:125], v[182:183], 2, s[14:15]
	global_load_dwordx4 v[174:177], v[124:125], off offset:16
	global_load_dwordx4 v[178:181], v[124:125], off
	v_add_f32_e64 v126, v108, -v102
	v_add_f32_e64 v127, v109, -v103
	v_fmac_f32_e32 v117, 0x3e38aa3b, v52
	v_cmp_le_i32_e32 vcc, v0, v154
	v_or_b32_e32 v160, 3, v0
	v_add_f32_e64 v122, v108, -v106
	v_add_f32_e64 v123, v109, -v107
	v_fmac_f32_e32 v137, 0x3e38aa3b, v53
	v_fma_f32 v138, v58, s24, v126
	v_fma_f32 v139, v59, s24, v127
	v_cndmask_b32_e32 v126, v216, v117, vcc
	v_cmp_lt_i32_e32 vcc, v0, v154
	v_or_b32_e32 v161, 2, v0
	v_fma_f32 v122, v54, s24, v122
	v_fma_f32 v123, v55, s24, v123
	v_cndmask_b32_e32 v127, v216, v137, vcc
	v_cmp_le_i32_e32 vcc, v160, v35
	v_or_b32_e32 v167, 7, v0
	v_or_b32_e32 v173, 6, v0
	v_cndmask_b32_e32 v125, v216, v123, vcc
	v_cmp_le_i32_e32 vcc, v161, v154
	v_or_b32_e32 v186, 17, v0
	v_or_b32_e32 v187, 19, v0
	v_cndmask_b32_e32 v124, v216, v122, vcc
	v_cmp_le_i32_e32 vcc, v167, v35
	v_or_b32_e32 v188, 18, v0
	v_or_b32_e32 v189, 21, v0
	v_cndmask_b32_e32 v123, v216, v139, vcc
	v_cmp_le_i32_e32 vcc, v173, v154
	v_or_b32_e32 v190, 20, v0
	v_or_b32_e32 v191, 23, v0
	v_cndmask_b32_e32 v122, v216, v138, vcc
	v_cmp_le_i32_e32 vcc, v186, v35
	v_or_b32_e32 v192, 22, v0
	v_or_b32_e32 v193, 33, v0
	v_max3_f32 v117, v126, s89, v127
	v_max3_f32 v117, v117, v124, v125
	v_max3_f32 v117, v117, v120, v121
	v_max3_f32 v117, v117, v122, v123
	v_or_b32_e32 v173, 55, v0
	s_mov_b64 s[52:53], 0
	s_waitcnt vmcnt(5)
	v_add_f32_e64 v128, v108, -v128
	v_add_f32_e64 v129, v109, -v129
	s_waitcnt vmcnt(4)
	v_add_f32_e64 v132, v108, -v132
	v_add_f32_e64 v133, v109, -v133
	v_add_f32_e64 v134, v108, -v134
	v_add_f32_e64 v135, v109, -v135
	v_fma_f32 v132, v60, s24, v132
	v_fma_f32 v133, v61, s24, v133
	v_fma_f32 v134, v62, s24, v134
	v_fma_f32 v135, v63, s24, v135
	v_cndmask_b32_e32 v161, v216, v133, vcc
	v_cmp_le_i32_e32 vcc, v136, v154
	s_waitcnt vmcnt(3)
	v_add_f32_e64 v138, v108, -v156
	v_add_f32_e64 v139, v109, -v157
	v_fma_f32 v128, v64, s24, v128
	v_fma_f32 v129, v65, s24, v129
	v_cndmask_b32_e32 v160, v216, v132, vcc
	v_cmp_le_i32_e32 vcc, v187, v35
	v_add_f32_e64 v130, v108, -v130
	v_add_f32_e64 v131, v109, -v131
	v_fma_f32 v184, v36, s24, v138
	v_fma_f32 v185, v37, s24, v139
	v_cndmask_b32_e32 v157, v216, v135, vcc
	v_cmp_le_i32_e32 vcc, v188, v154
	v_fma_f32 v130, v66, s24, v130
	v_fma_f32 v131, v67, s24, v131
	v_max3_f32 v117, v117, v160, v161
	v_cndmask_b32_e32 v156, v216, v134, vcc
	v_cmp_le_i32_e32 vcc, v189, v35
	v_max3_f32 v117, v117, v156, v157
	v_or_b32_e32 v132, 50, v0
	v_cndmask_b32_e32 v139, v216, v129, vcc
	v_cmp_le_i32_e32 vcc, v190, v154
	v_or_b32_e32 v133, 52, v0
	s_nop 0
	v_cndmask_b32_e32 v138, v216, v128, vcc
	v_cmp_le_i32_e32 vcc, v191, v35
	v_add_f32_e64 v128, v108, -v158
	v_add_f32_e64 v129, v109, -v159
	v_max3_f32 v117, v117, v138, v139
	v_cndmask_b32_e32 v135, v216, v131, vcc
	v_cmp_le_i32_e32 vcc, v192, v154
	v_or_b32_e32 v131, 34, v0
	v_fma_f32 v128, v38, s24, v128
	v_fma_f32 v129, v39, s24, v129
	v_cndmask_b32_e32 v134, v216, v130, vcc
	v_cmp_le_i32_e32 vcc, v193, v35
	v_or_b32_e32 v130, 35, v0
	v_max3_f32 v117, v117, v134, v135
	v_cndmask_b32_e32 v137, v216, v185, vcc
	v_cmp_le_i32_e32 vcc, v166, v154
	s_nop 1
	v_cndmask_b32_e32 v136, v216, v184, vcc
	v_cmp_le_i32_e32 vcc, v130, v35
	v_or_b32_e32 v130, 37, v0
	v_max3_f32 v117, v117, v136, v137
	v_cndmask_b32_e32 v159, v216, v129, vcc
	v_cmp_le_i32_e32 vcc, v131, v154
	v_or_b32_e32 v131, 36, v0
	s_nop 0
	v_cndmask_b32_e32 v158, v216, v128, vcc
	s_waitcnt vmcnt(2)
; template <int DV, bool FOX>
; DI void flash(f32x16 (&O)[DV / 32], const bf16_t* __restrict__ qptr, const bf16_t* __restrict__ kg, const bf16_t* __restrict__ vtg,
;               int ntiles, int q, float slope2, const float* __restrict__ cum2, float KN, bf16_t* smem) {
;     ...
;         if (kb + 63 < qlo) {
; #pragma unroll
;             for (int sub = 0; sub < 2; ++sub) {
; #pragma unroll
;                 for (int i8 = 0; i8 < 2; ++i8) {
;                     const int k0 = kb + sub * 32 + 16 * i8 + 8 * h;
;                     float ck[8];
;                     float base = 0.f;
;                     if (FOX) {
;                         const f32x4 c0 = *(const f32x4*)(cum2 + k0), c1v = *(const f32x4*)(cum2 + k0 + 4);
;                         ck[0] = c0[0]; ck[1] = c0[1]; ck[2] = c0[2]; ck[3] = c0[3]; ck[4] = c1v[0]; ck[5] = c1v[1]; ck[6] = c1v[2]; ck[7] = c1v[3];
;                     } else base = -slope2 * (float)(q - k0);
; #pragma unroll
;                     for (int e = 0; e < 8; ++e) {
;                         const float bias = FOX ? cq - ck[e] : fmaf(slope2, (float)e, base);
;                         const float t = fmaf(s[sub][8 * i8 + e], c1, bias);
;                         s[sub][8 * i8 + e] = t;
;                         mx = fmaxf(mx, t);
;                     }
;                 }
;             }
;         } else {
; #pragma unroll
;             for (int sub = 0; sub < 2; ++sub) {
; #pragma unroll
;                 for (int i8 = 0; i8 < 2; ++i8) {
;                     const int k0 = kb + sub * 32 + 16 * i8 + 8 * h;
;                     float ck[8];
;                     if (FOX) {
;                         const f32x4 c0 = *(const f32x4*)(cum2 + k0), c1v = *(const f32x4*)(cum2 + k0 + 4);
;                         ck[0] = c0[0]; ck[1] = c0[1]; ck[2] = c0[2]; ck[3] = c0[3]; ck[4] = c1v[0]; ck[5] = c1v[1]; ck[6] = c1v[2]; ck[7] = c1v[3];
;                     }
; #pragma unroll
;                     for (int e = 0; e < 8; ++e) {
;                         const int k = k0 + e;
;                         float t = s[sub][8 * i8 + e] * c1;
;                         if (FOX) t += cq - ck[e];
;                         else t -= slope2 * fabsf((float)(q - k));
;                         t = (k < kend) ? t : -INFINITY;
;                         s[sub][8 * i8 + e] = t;
;                         mx = fmaxf(mx, t);
;                     }
	v_add_f32_e64 v128, v108, -v162
	v_add_f32_e64 v129, v109, -v163
	v_cmp_le_i32_e32 vcc, v130, v35
	v_fma_f32 v128, v40, s24, v128
	v_fma_f32 v129, v41, s24, v129
	v_or_b32_e32 v130, 39, v0
	v_cndmask_b32_e32 v163, v216, v129, vcc
	v_cmp_le_i32_e32 vcc, v131, v154
	v_or_b32_e32 v131, 38, v0
	v_max3_f32 v117, v117, v158, v159
	v_cndmask_b32_e32 v162, v216, v128, vcc
	v_add_f32_e64 v128, v108, -v164
	v_add_f32_e64 v129, v109, -v165
	v_cmp_le_i32_e32 vcc, v130, v35
	v_fma_f32 v128, v42, s24, v128
	v_fma_f32 v129, v43, s24, v129
	v_or_b32_e32 v130, 49, v0
	v_cndmask_b32_e32 v165, v216, v129, vcc
	v_cmp_le_i32_e32 vcc, v131, v154
	v_max3_f32 v117, v117, v162, v163
	s_nop 0
	v_cndmask_b32_e32 v164, v216, v128, vcc
	s_waitcnt vmcnt(0)
	v_add_f32_e64 v128, v108, -v178
	v_add_f32_e64 v129, v109, -v179
	v_cmp_le_i32_e32 vcc, v130, v35
	v_fma_f32 v128, v44, s24, v128
	v_fma_f32 v129, v45, s24, v129
	v_or_b32_e32 v130, 51, v0
	v_cndmask_b32_e32 v167, v216, v129, vcc
	v_cmp_le_i32_e32 vcc, v182, v154
	v_max3_f32 v117, v117, v164, v165
	s_nop 0
	v_cndmask_b32_e32 v166, v216, v128, vcc
	v_add_f32_e64 v128, v108, -v180
	v_add_f32_e64 v129, v109, -v181
	v_cmp_le_i32_e32 vcc, v130, v35
	v_fma_f32 v128, v46, s24, v128
	v_fma_f32 v129, v47, s24, v129
	v_max3_f32 v117, v117, v166, v167
	v_cndmask_b32_e32 v131, v216, v129, vcc
	v_cmp_le_i32_e32 vcc, v132, v154
	v_or_b32_e32 v132, 53, v0
	v_or_b32_e32 v0, 54, v0
	v_cndmask_b32_e32 v130, v216, v128, vcc
	v_add_f32_e64 v128, v108, -v174
	v_add_f32_e64 v129, v109, -v175
	v_cmp_le_i32_e32 vcc, v132, v35
	v_fma_f32 v128, v48, s24, v128
	v_fma_f32 v129, v49, s24, v129
	v_max3_f32 v117, v117, v130, v131
	v_cndmask_b32_e32 v129, v216, v129, vcc
	v_cmp_le_i32_e32 vcc, v133, v154
	v_add_f32_e64 v132, v108, -v176
	v_add_f32_e64 v133, v109, -v177
	s_nop 0
	v_cndmask_b32_e32 v128, v216, v128, vcc
	v_fma_f32 v132, v50, s24, v132
	v_fma_f32 v133, v51, s24, v133
	v_cmp_le_i32_e32 vcc, v173, v35
	v_max3_f32 v117, v117, v128, v129
	s_nop 0
	v_cndmask_b32_e32 v133, v216, v133, vcc
	v_cmp_le_i32_e32 vcc, v0, v154
	s_nop 1
	v_cndmask_b32_e32 v132, v216, v132, vcc
	v_max3_f32 v117, v117, v132, v133
.LBB0_703:
	s_andn2_b64 vcc, exec, s[52:53]
	s_cbranch_vccnz .LBB0_705
	global_load_dwordx4 v[128:131], v[118:119], off offset:64
	global_load_dwordx4 v[132:135], v[118:119], off offset:80
	global_load_dwordx4 v[136:139], v[118:119], off offset:128
	global_load_dwordx4 v[156:159], v[118:119], off offset:144
	global_load_dwordx4 v[160:163], v[118:119], off offset:192
	global_load_dwordx4 v[164:167], v[118:119], off offset:208
	s_waitcnt vmcnt(6)
	v_add_f32_e64 v104, v108, -v104
	v_add_f32_e64 v105, v109, -v105
	v_add_f32_e64 v106, v108, -v106
	v_add_f32_e64 v107, v109, -v107
	v_fma_f32 v126, v52, s24, v104
	v_fma_f32 v127, v53, s24, v105
	v_fma_f32 v124, v54, s24, v106
	v_fma_f32 v125, v55, s24, v107
	v_max3_f32 v0, v126, s89, v127
	v_fma_f32 v120, v56, s24, v100
	v_fma_f32 v121, v57, s24, v101
	v_add_f32_e64 v56, v108, -v102
	v_add_f32_e64 v57, v109, -v103
	v_max3_f32 v0, v0, v124, v125
	v_fma_f32 v122, v58, s24, v56
	v_fma_f32 v123, v59, s24, v57
	v_max3_f32 v0, v0, v120, v121
	v_max3_f32 v0, v0, v122, v123
	s_waitcnt vmcnt(5)
	v_add_f32_e64 v52, v108, -v128
	v_add_f32_e64 v53, v109, -v129
	v_add_f32_e64 v54, v108, -v130
	v_add_f32_e64 v55, v109, -v131
	s_waitcnt vmcnt(4)
	v_add_f32_e64 v56, v108, -v132
	v_add_f32_e64 v57, v109, -v133
	s_waitcnt vmcnt(2)
	v_add_f32_e64 v104, v108, -v156
	v_add_f32_e64 v105, v109, -v157
	s_waitcnt vmcnt(1)
	v_add_f32_e64 v118, v108, -v160
	v_add_f32_e64 v119, v109, -v161
	v_fma_f32 v160, v60, s24, v52
	v_fma_f32 v161, v61, s24, v53
	v_fma_f32 v156, v62, s24, v54
	v_fma_f32 v157, v63, s24, v55
	v_max3_f32 v0, v0, v160, v161
	v_add_f32_e64 v58, v108, -v134
	v_add_f32_e64 v59, v109, -v135
	v_add_f32_e64 v102, v108, -v138
	v_add_f32_e64 v103, v109, -v139
	v_fma_f32 v138, v64, s24, v56
	v_fma_f32 v139, v65, s24, v57
	v_max3_f32 v0, v0, v156, v157
	v_add_f32_e64 v100, v108, -v136
	v_add_f32_e64 v101, v109, -v137
	v_fma_f32 v134, v66, s24, v58
	v_fma_f32 v135, v67, s24, v59
	v_max3_f32 v0, v0, v138, v139
	v_fma_f32 v136, v36, s24, v100
	v_fma_f32 v137, v37, s24, v101
	v_max3_f32 v0, v0, v134, v135
	v_add_f32_e64 v106, v108, -v158
	v_add_f32_e64 v107, v109, -v159
	v_fma_f32 v158, v38, s24, v102
	v_fma_f32 v159, v39, s24, v103
	v_max3_f32 v0, v0, v136, v137
	v_add_f32_e64 v128, v108, -v162
	v_add_f32_e64 v129, v109, -v163
	v_fma_f32 v162, v40, s24, v104
	v_fma_f32 v163, v41, s24, v105
	v_max3_f32 v0, v0, v158, v159
	s_waitcnt vmcnt(0)
	v_add_f32_e64 v132, v108, -v164
	v_add_f32_e64 v133, v109, -v165
	v_fma_f32 v164, v42, s24, v106
	v_fma_f32 v165, v43, s24, v107
	v_max3_f32 v0, v0, v162, v163
	v_add_f32_e64 v174, v108, -v166
	v_add_f32_e64 v175, v109, -v167
	v_fma_f32 v166, v44, s24, v118
	v_fma_f32 v167, v45, s24, v119
	v_max3_f32 v0, v0, v164, v165
	v_fma_f32 v130, v46, s24, v128
	v_fma_f32 v131, v47, s24, v129
	v_max3_f32 v0, v0, v166, v167
	v_fma_f32 v128, v48, s24, v132
	v_fma_f32 v129, v49, s24, v133
	v_max3_f32 v0, v0, v130, v131
	v_max3_f32 v0, v0, v128, v129
	v_fma_f32 v132, v50, s24, v174
	v_fma_f32 v133, v51, s24, v175
	s_nop 0
	v_max3_f32 v117, v0, v132, v133
.LBB0_705:
	v_mov_b32_e32 v0, v117
	s_nop 1
	v_permlane32_swap_b32_e32 v117, v0
	v_max3_f32 v117, v172, v117, v0
	v_cmp_gt_f32_e32 vcc, v117, v172
	s_cbranch_vccz .LBB0_707
	v_sub_f32_e32 v0, v172, v117
	v_exp_f32_e32 v0, v0
	s_nop 0
	v_mul_f32_e64 v16, v16, v0
	v_mul_f32_e64 v17, v17, v0
	v_mul_f32_e64 v14, v14, v0
	v_mul_f32_e64 v15, v15, v0
	v_mul_f32_e64 v12, v12, v0
	v_mul_f32_e64 v13, v13, v0
	v_mul_f32_e64 v10, v10, v0
	v_mul_f32_e64 v11, v11, v0
	v_mul_f32_e64 v8, v8, v0
	v_mul_f32_e64 v9, v9, v0
	v_mul_f32_e64 v6, v6, v0
	v_mul_f32_e64 v7, v7, v0
	v_mul_f32_e64 v4, v4, v0
	v_mul_f32_e64 v5, v5, v0
	v_mul_f32_e64 v2, v2, v0
	v_mul_f32_e64 v3, v3, v0
	v_mul_f32_e64 v32, v32, v0
	v_mul_f32_e64 v33, v33, v0
	v_mul_f32_e64 v30, v30, v0
	v_mul_f32_e64 v31, v31, v0
	v_mul_f32_e64 v28, v28, v0
	v_mul_f32_e64 v29, v29, v0
	v_mul_f32_e64 v26, v26, v0
	v_mul_f32_e64 v27, v27, v0
	v_mul_f32_e64 v24, v24, v0
	v_mul_f32_e64 v25, v25, v0
	v_mul_f32_e64 v22, v22, v0
	v_mul_f32_e64 v23, v23, v0
	v_mul_f32_e64 v20, v20, v0
	v_mul_f32_e64 v21, v21, v0
	v_mul_f32_e64 v18, v18, v0
	v_mul_f32_e64 v19, v19, v0
	v_mul_f32_e32 v34, v34, v0

; template <int DV, bool FOX>
; DI void flash(f32x16 (&O)[DV / 32], const bf16_t* __restrict__ qptr, const bf16_t* __restrict__ kg, const bf16_t* __restrict__ vtg,
;               int ntiles, int q, float slope2, const float* __restrict__ cum2, float KN, bf16_t* smem) {
;     ...
;         if (kt > 0) {
;             const int klast = kb - 1;
;             float bm = 0.f;
;             if (klast < q) bm = FOX ? cq - cklast : -slope2 * (float)(q - klast);
;             const bool pred = (q >= LT) || (sbound + bm < m - 152.f);
;             wskip = __all(pred);
;         }
.LBB0_710:
	s_waitcnt vmcnt(0)
	v_sub_f32_e32 v0, v108, v142
	v_cmp_le_i32_e32 vcc, s70, v154
	s_nop 1
	v_cndmask_b32_e32 v142, 0, v0, vcc
	v_add_f32_e64 v36, v116, v142
	v_add_f32_e64 v37, v117, v143
	s_nop 0
	v_cmp_lt_f32_e32 vcc, v36, v37
	s_or_b64 s[10:11], s[4:5], vcc
	v_cndmask_b32_e64 v0, 0, 1, s[10:11]
	v_cmp_ne_u32_e32 vcc, 0, v0
	s_cmp_eq_u64 vcc, exec
	s_cselect_b64 s[10:11], -1, 0

; DI unsigned cvt_pk(float lo, float hi) { f32x2 v = {lo, hi}; bf16x2v b = __builtin_convertvector(v, bf16x2v); return __builtin_bit_cast(unsigned, b); }
; DI float xsum32(float x) { auto r = __builtin_amdgcn_permlane32_swap(__float_as_uint(x), __float_as_uint(x), false, false); return __uint_as_float(r[0]) + __uint_as_float(r[1]); }
; template <int DV, bool FOX>
; DI void flash(f32x16 (&O)[DV / 32], const bf16_t* __restrict__ qptr, const bf16_t* __restrict__ kg, const bf16_t* __restrict__ vtg,
;               int ntiles, int q, float slope2, const float* __restrict__ cum2, float KN, bf16_t* smem) {
;     ...
;     l = xsum32(l);
;     const float inv = 1.0f / l;
; #pragma unroll
;     for (int dt = 0; dt < NDT; ++dt)
; #pragma unroll
;         for (int i = 0; i < 16; ++i) O[dt][i] *= inv;
; DI void ph_attn(const Params& p, bf16_t* smem, int* s_item) {
;     ...
;             if (q < LT) {
;                 bf16_t* d = MIX + qrow * 1024 + 512 + hf * 64;
; #pragma unroll
;                 for (int dt = 0; dt < 2; ++dt)
; #pragma unroll
;                     for (int g = 0; g < 4; ++g) {
;                         const int dv = dt * 32 + 8 * g + 4 * h;
;                         u32x2 wv; wv[0] = cvt_pk(O[dt][4 * g], O[dt][4 * g + 1]); wv[1] = cvt_pk(O[dt][4 * g + 2], O[dt][4 * g + 3]);
;                         *(u32x2*)(d + dv) = wv;
;                     }
.LBB0_724:
	v_mov_b32_e32 v0, v34
	s_lshl_b32 s6, s91, 6
	s_nop 0
	v_permlane32_swap_b32_e32 v34, v0
	v_cmp_gt_i32_e32 vcc, s25, v154
	s_and_saveexec_b64 s[4:5], vcc
	s_xor_b64 s[4:5], exec, s[4:5]
	s_cbranch_execz .LBB0_593
	v_add_f32_e32 v0, v34, v0
	v_div_scale_f32 v34, s[8:9], v0, v0, 1.0
	v_rcp_f32_e32 v35, v34
	v_div_scale_f32 v36, vcc, 1.0, v0, 1.0
	s_lshl_b32 s20, s6, 1
	v_fma_f32 v37, -v34, v35, 1.0
	v_fmac_f32_e32 v35, v37, v35
	v_mul_f32_e32 v37, v36, v35
	v_fma_f32 v38, -v34, v37, v36
	v_fmac_f32_e32 v37, v38, v35
	v_fma_f32 v34, -v34, v37, v36
	v_div_fmas_f32 v34, v34, v35, v37
	v_div_fixup_f32 v0, v34, v0, 1.0
	v_lshlrev_b64 v[34:35], 11, v[152:153]
	v_lshl_add_u64 v[34:35], s[40:41], 0, v[34:35]
	v_mul_f32_e64 v32, v32, v0
	v_mul_f32_e64 v33, v33, v0
	v_mul_f32_e64 v30, v30, v0
	v_mul_f32_e64 v31, v31, v0
	v_mul_f32_e64 v28, v28, v0
	v_mul_f32_e64 v29, v29, v0
	v_mul_f32_e64 v26, v26, v0
	v_mul_f32_e64 v27, v27, v0
	v_mul_f32_e64 v24, v24, v0
	v_mul_f32_e64 v25, v25, v0
	v_mul_f32_e64 v22, v22, v0
	v_mul_f32_e64 v23, v23, v0
	v_mul_f32_e64 v20, v20, v0
	v_mul_f32_e64 v21, v21, v0
	v_mul_f32_e64 v18, v18, v0
	v_mul_f32_e64 v19, v19, v0
	v_mul_f32_e64 v16, v16, v0
	v_mul_f32_e64 v17, v17, v0
	v_mul_f32_e64 v14, v14, v0
	v_mul_f32_e64 v15, v15, v0
	v_mul_f32_e64 v12, v12, v0
	v_mul_f32_e64 v13, v13, v0
	v_mul_f32_e64 v10, v10, v0
	v_mul_f32_e64 v11, v11, v0
	v_mul_f32_e64 v8, v8, v0
	v_mul_f32_e64 v9, v9, v0
	v_mul_f32_e64 v6, v6, v0
	v_mul_f32_e64 v7, v7, v0
	v_mul_f32_e64 v4, v4, v0
	v_mul_f32_e64 v5, v5, v0
	v_mul_f32_e64 v2, v2, v0
	v_mul_f32_e64 v3, v3, v0
	v_lshl_add_u64 v[34:35], v[34:35], 0, s[20:21]
	v_lshlrev_b32_e32 v0, 1, v144
	v_cvt_pk_bf16_f32 v2, v2, v3
	v_cvt_pk_bf16_f32 v3, v4, v5
	v_lshl_add_u64 v[4:5], v[34:35], 0, v[0:1]
	global_store_dwordx2 v[4:5], v[2:3], off offset:1024
	v_cvt_pk_bf16_f32 v2, v6, v7
	v_cvt_pk_bf16_f32 v3, v8, v9
	global_store_dwordx2 v[4:5], v[2:3], off offset:1040
	v_cvt_pk_bf16_f32 v2, v10, v11
	v_cvt_pk_bf16_f32 v3, v12, v13
	global_store_dwordx2 v[4:5], v[2:3], off offset:1056
	v_cvt_pk_bf16_f32 v2, v14, v15
	v_cvt_pk_bf16_f32 v3, v16, v17
	global_store_dwordx2 v[4:5], v[2:3], off offset:1072
	v_cvt_pk_bf16_f32 v2, v18, v19
	v_cvt_pk_bf16_f32 v3, v20, v21
	global_store_dwordx2 v[4:5], v[2:3], off offset:1088
	v_cvt_pk_bf16_f32 v2, v22, v23
	v_cvt_pk_bf16_f32 v3, v24, v25
	global_store_dwordx2 v[4:5], v[2:3], off offset:1104
	v_cvt_pk_bf16_f32 v2, v26, v27
	v_cvt_pk_bf16_f32 v3, v28, v29
	global_store_dwordx2 v[4:5], v[2:3], off offset:1120
	v_cvt_pk_bf16_f32 v2, v30, v31
	v_cvt_pk_bf16_f32 v3, v32, v33
	global_store_dwordx2 v[4:5], v[2:3], off offset:1136
	s_branch .LBB0_593
